# fused-LN epilogue: the four agent-scope loads of LN partial statistics per row issued together (one wait) instead of four serial round trips; same summation order
# baseline (speedup 1.0000x reference)
; #define GAS __attribute__((address_space(1)))
; DI unsigned pk2(float lo, float hi) { f32x2 v = {lo, hi}; bf16x2v b = __builtin_convertvector(v, bf16x2v); return __builtin_bit_cast(unsigned, b); }
;   DI void full(const int mt_, const int nt_, f32x16 (&acc)[2][2][2], const int tw, const int fw, const int r, const int hh, char* lds, const int tid) const {
;     ...
; #pragma unroll
;     for (int mt = 0; mt < 2; ++mt) {
;       const int tl = tw * 64 + mt * 32 + r;
;       float S = 0.f, Q = 0.f;
; #pragma unroll
;       for (int k = 0; k < 4; ++k) {
;         const unsigned long long pk = __hip_atomic_load((GAS unsigned long long*)(xchg + ((size_t)(mt_ * 4 + k) * 256 + tl) * 2), __ATOMIC_RELAXED, __HIP_MEMORY_SCOPE_AGENT);
;         S += __uint_as_float((unsigned)pk);
;         Q += __uint_as_float((unsigned)(pk >> 32));
;       }
;       const float mean = S * (1.f / 1024.f);
;       const float rstd = rsqrtf(fmaxf(Q * (1.f / 1024.f) - mean * mean, 0.f) + 1e-5f);
;       const int c0 = nt_ * 256 + fw * 128 + 16 * hh;
;       const size_t rowo = (size_t)(mt_ * 256 + tl) * 1024 + c0;
; #pragma unroll
;       for (int half = 0; half < 2; ++half)
; #pragma unroll
;         for (int nt = 0; nt < 2; ++nt) {
; #pragma unroll
;           for (int gp = 0; gp < 2; ++gp) {
;             const int co = half * 64 + nt * 32 + 8 * gp;
;             u32x4 ob;
; #pragma unroll
;             for (int h2 = 0; h2 < 2; ++h2) {
;               f32x4 gv = *(const f32x4*)(g + c0 + co + 4 * h2), bv = *(const f32x4*)(b + c0 + co + 4 * h2), o;
; #pragma unroll
;               for (int jj = 0; jj < 4; ++jj) o[jj] = (acc[half][nt][mt][8 * gp + 4 * h2 + jj] - mean) * rstd * gv[jj] + bv[jj];
;               *(f32x4*)(xout + rowo + co + 4 * h2) = o;
;               ob[2 * h2] = pk2(o[0], o[1]); ob[2 * h2 + 1] = pk2(o[2], o[3]);
;             }
;             *(u32x4*)(xb + rowo + co) = ob;
;           }
;           __builtin_amdgcn_sched_barrier(0);
;         }
;     }
;     __syncthreads();
.LBB0_267:
	s_or_b64 exec, exec, s[20:21]
	s_lshl_b32 s96, s2, 2
	s_lshl_b64 s[2:3], s[96:97], 11
	v_lshlrev_b64 v[12:13], 10, v[0:1]
	v_lshlrev_b32_e32 v0, 4, v224
	v_add_u32_e32 v14, s48, v182
	s_add_u32 s20, s6, s2
	v_or_b32_e32 v16, v0, v14
	s_addc_u32 s21, s7, s3
	v_lshlrev_b32_e32 v0, 3, v223
	s_barrier
	global_load_dwordx2 v[32:33], v0, s[20:21] sc1
	s_or_b32 s2, s96, 1
	s_mov_b32 s3, s97
	s_lshl_b64 s[2:3], s[2:3], 11
	s_add_u32 s22, s6, s2
	s_addc_u32 s23, s7, s3
	s_or_b32 s2, s96, 2
	s_mov_b32 s3, s97
	s_lshl_b64 s[2:3], s[2:3], 11
	s_add_u32 s24, s6, s2
	s_addc_u32 s25, s7, s3
	s_or_b32 s96, s96, 3
	s_lshl_b64 s[2:3], s[96:97], 11
	s_add_u32 s26, s6, s2
	s_addc_u32 s27, s7, s3
	v_ashrrev_i32_e32 v17, 31, v16
	v_lshl_add_u64 v[48:49], v[12:13], 0, v[16:17]
	global_load_dwordx2 v[50:51], v0, s[22:23] sc1
	global_load_dwordx2 v[52:53], v0, s[24:25] sc1
	global_load_dwordx2 v[14:15], v0, s[26:27] sc1
	s_waitcnt vmcnt(0)
	v_add_f32_e32 v30, 0, v32
	v_add_f32_e32 v31, 0, v33
	v_add_f32_e32 v30, v30, v50
	v_add_f32_e32 v31, v31, v51
	v_add_f32_e32 v30, v30, v52
	v_add_f32_e32 v31, v31, v53
	v_add_f32_e32 v0, v30, v14
	v_mul_f32_e32 v0, 0x3a800000, v0
	v_add_f32_e32 v14, v31, v15
	v_mul_f32_e32 v15, v0, v0
	v_fma_f32 v14, v14, s67, -v15
	v_max_f32_e32 v14, 0, v14
	v_add_f32_e32 v14, 0x3727c5ac, v14
	v_cmp_gt_f32_e32 vcc, s63, v14
	v_mul_f32_e32 v15, 0x4b800000, v14
	v_pk_add_f32 v[32:33], v[178:179], v[0:1] op_sel_hi:[1,0] neg_lo:[0,1] neg_hi:[0,1]
	v_cndmask_b32_e32 v14, v14, v15, vcc
	v_rsq_f32_e32 v14, v14
	s_nop 0
	v_mul_f32_e32 v15, 0x45800000, v14
	v_cndmask_b32_e32 v30, v14, v15, vcc
	v_lshlrev_b64 v[14:15], 2, v[16:17]
	v_lshl_add_u64 v[12:13], s[14:15], 0, v[14:15]
	v_lshl_add_u64 v[14:15], s[16:17], 0, v[14:15]
	global_load_dwordx4 v[50:53], v[12:13], off
	global_load_dwordx4 v[74:77], v[14:15], off
	v_pk_mul_f32 v[32:33], v[32:33], v[30:31] op_sel_hi:[1,0]
	s_waitcnt vmcnt(0)
	v_pk_fma_f32 v[50:51], v[50:51], v[32:33], v[74:75]
	v_pk_add_f32 v[32:33], v[180:181], v[0:1] op_sel_hi:[1,0] neg_lo:[0,1] neg_hi:[0,1]
	s_nop 0
	v_pk_mul_f32 v[32:33], v[32:33], v[30:31] op_sel_hi:[1,0]
	s_nop 0
	v_pk_fma_f32 v[52:53], v[52:53], v[32:33], v[76:77]
	v_lshl_add_u64 v[32:33], v[48:49], 2, s[8:9]
	global_store_dwordx4 v[32:33], v[50:53], off
	global_load_dwordx4 v[74:77], v[12:13], off offset:16
	global_load_dwordx4 v[78:81], v[14:15], off offset:16
	v_cvt_pk_bf16_f32 v50, v50, v51
	v_cvt_pk_bf16_f32 v51, v52, v53
	v_pk_add_f32 v[52:53], v[158:159], v[0:1] op_sel_hi:[1,0] neg_lo:[0,1] neg_hi:[0,1]
	v_lshl_add_u64 v[48:49], v[48:49], 1, s[12:13]
	v_pk_mul_f32 v[52:53], v[52:53], v[30:31] op_sel_hi:[1,0]
	s_waitcnt vmcnt(0)
	v_pk_fma_f32 v[74:75], v[74:75], v[52:53], v[78:79]
	v_pk_add_f32 v[52:53], v[160:161], v[0:1] op_sel_hi:[1,0] neg_lo:[0,1] neg_hi:[0,1]
	v_pk_add_f32 v[78:79], v[154:155], v[0:1] op_sel_hi:[1,0] neg_lo:[0,1] neg_hi:[0,1]
	v_pk_mul_f32 v[52:53], v[52:53], v[30:31] op_sel_hi:[1,0]
	v_pk_mul_f32 v[78:79], v[78:79], v[30:31] op_sel_hi:[1,0]
	v_pk_fma_f32 v[76:77], v[76:77], v[52:53], v[80:81]
	v_cvt_pk_bf16_f32 v52, v74, v75
	v_cvt_pk_bf16_f32 v53, v76, v77
	global_store_dwordx4 v[32:33], v[74:77], off offset:16
	global_store_dwordx4 v[48:49], v[50:53], off
	global_load_dwordx4 v[50:53], v[12:13], off offset:32
	s_nop 0
	global_load_dwordx4 v[74:77], v[14:15], off offset:32
	s_waitcnt vmcnt(0)
	v_pk_fma_f32 v[50:51], v[50:51], v[78:79], v[74:75]
	v_pk_add_f32 v[74:75], v[156:157], v[0:1] op_sel_hi:[1,0] neg_lo:[0,1] neg_hi:[0,1]
	s_nop 0
	v_pk_mul_f32 v[74:75], v[74:75], v[30:31] op_sel_hi:[1,0]
	s_nop 0
	v_pk_fma_f32 v[52:53], v[52:53], v[74:75], v[76:77]
	global_store_dwordx4 v[32:33], v[50:53], off offset:32
	global_load_dwordx4 v[74:77], v[12:13], off offset:48
	global_load_dwordx4 v[78:81], v[14:15], off offset:48
	v_cvt_pk_bf16_f32 v50, v50, v51
	v_cvt_pk_bf16_f32 v51, v52, v53
	v_pk_add_f32 v[52:53], v[152:153], v[0:1] op_sel_hi:[1,0] neg_lo:[0,1] neg_hi:[0,1]
	s_nop 0
	v_pk_mul_f32 v[52:53], v[52:53], v[30:31] op_sel_hi:[1,0]
	s_waitcnt vmcnt(0)
	v_pk_fma_f32 v[74:75], v[74:75], v[52:53], v[78:79]
	v_pk_add_f32 v[52:53], v[150:151], v[0:1] op_sel_hi:[1,0] neg_lo:[0,1] neg_hi:[0,1]
	s_nop 0
	v_pk_mul_f32 v[52:53], v[52:53], v[30:31] op_sel_hi:[1,0]
	s_nop 0
	v_pk_fma_f32 v[76:77], v[76:77], v[52:53], v[80:81]
	v_cvt_pk_bf16_f32 v52, v74, v75
	v_cvt_pk_bf16_f32 v53, v76, v77
	global_store_dwordx4 v[32:33], v[74:77], off offset:48
	global_store_dwordx4 v[48:49], v[50:53], off offset:16
	global_load_dwordx4 v[50:53], v[12:13], off offset:128
	s_nop 0
	global_load_dwordx4 v[74:77], v[14:15], off offset:128
	v_pk_add_f32 v[78:79], v[144:145], v[0:1] op_sel_hi:[1,0] neg_lo:[0,1] neg_hi:[0,1]
	v_pk_add_f32 v[80:81], v[148:149], v[0:1] op_sel_hi:[1,0] neg_lo:[0,1] neg_hi:[0,1]
	v_pk_mul_f32 v[78:79], v[78:79], v[30:31] op_sel_hi:[1,0]
	v_pk_mul_f32 v[80:81], v[80:81], v[30:31] op_sel_hi:[1,0]
	v_pk_add_f32 v[82:83], v[138:139], v[0:1] op_sel_hi:[1,0] neg_lo:[0,1] neg_hi:[0,1]
	v_pk_add_f32 v[84:85], v[146:147], v[0:1] op_sel_hi:[1,0] neg_lo:[0,1] neg_hi:[0,1]
	v_pk_mul_f32 v[82:83], v[82:83], v[30:31] op_sel_hi:[1,0]
	v_pk_mul_f32 v[84:85], v[84:85], v[30:31] op_sel_hi:[1,0]
	s_waitcnt vmcnt(0)
	v_pk_fma_f32 v[50:51], v[78:79], v[50:51], v[74:75]
	v_pk_fma_f32 v[52:53], v[80:81], v[52:53], v[76:77]
	global_store_dwordx4 v[32:33], v[50:53], off offset:128
	global_load_dwordx4 v[74:77], v[12:13], off offset:144
	global_load_dwordx4 v[78:81], v[14:15], off offset:144
	v_cvt_pk_bf16_f32 v50, v50, v51
	v_cvt_pk_bf16_f32 v51, v52, v53
	s_waitcnt vmcnt(0)
; DI unsigned pk2(float lo, float hi) { f32x2 v = {lo, hi}; bf16x2v b = __builtin_convertvector(v, bf16x2v); return __builtin_bit_cast(unsigned, b); }
;   DI void full(const int mt_, const int nt_, f32x16 (&acc)[2][2][2], const int tw, const int fw, const int r, const int hh, char* lds, const int tid) const {
;     ...
; #pragma unroll
;       for (int half = 0; half < 2; ++half)
; #pragma unroll
;         for (int nt = 0; nt < 2; ++nt) {
; #pragma unroll
;           for (int gp = 0; gp < 2; ++gp) {
;             const int co = half * 64 + nt * 32 + 8 * gp;
;             u32x4 ob;
; #pragma unroll
;             for (int h2 = 0; h2 < 2; ++h2) {
;               f32x4 gv = *(const f32x4*)(g + c0 + co + 4 * h2), bv = *(const f32x4*)(b + c0 + co + 4 * h2), o;
; #pragma unroll
;               for (int jj = 0; jj < 4; ++jj) o[jj] = (acc[half][nt][mt][8 * gp + 4 * h2 + jj] - mean) * rstd * gv[jj] + bv[jj];
;               *(f32x4*)(xout + rowo + co + 4 * h2) = o;
;               ob[2 * h2] = pk2(o[0], o[1]); ob[2 * h2 + 1] = pk2(o[2], o[3]);
;             }
;             *(u32x4*)(xb + rowo + co) = ob;
;           }
;           __builtin_amdgcn_sched_barrier(0);
;         }
	v_pk_fma_f32 v[74:75], v[82:83], v[74:75], v[78:79]
	v_pk_fma_f32 v[76:77], v[84:85], v[76:77], v[80:81]
	v_cvt_pk_bf16_f32 v52, v74, v75
	v_cvt_pk_bf16_f32 v53, v76, v77
	global_store_dwordx4 v[32:33], v[74:77], off offset:144
	global_store_dwordx4 v[48:49], v[50:53], off offset:64
	global_load_dwordx4 v[50:53], v[12:13], off offset:160
	s_nop 0
	global_load_dwordx4 v[74:77], v[14:15], off offset:160
	v_pk_add_f32 v[78:79], v[130:131], v[0:1] op_sel_hi:[1,0] neg_lo:[0,1] neg_hi:[0,1]
	v_pk_add_f32 v[80:81], v[140:141], v[0:1] op_sel_hi:[1,0] neg_lo:[0,1] neg_hi:[0,1]
	v_pk_mul_f32 v[78:79], v[78:79], v[30:31] op_sel_hi:[1,0]
	v_pk_mul_f32 v[80:81], v[80:81], v[30:31] op_sel_hi:[1,0]
	v_pk_add_f32 v[82:83], v[124:125], v[0:1] op_sel_hi:[1,0] neg_lo:[0,1] neg_hi:[0,1]
	v_pk_add_f32 v[84:85], v[134:135], v[0:1] op_sel_hi:[1,0] neg_lo:[0,1] neg_hi:[0,1]
	v_pk_mul_f32 v[82:83], v[82:83], v[30:31] op_sel_hi:[1,0]
	v_pk_mul_f32 v[84:85], v[84:85], v[30:31] op_sel_hi:[1,0]
	s_waitcnt vmcnt(0)
	v_pk_fma_f32 v[50:51], v[78:79], v[50:51], v[74:75]
	v_pk_fma_f32 v[52:53], v[80:81], v[52:53], v[76:77]
	global_store_dwordx4 v[32:33], v[50:53], off offset:160
	global_load_dwordx4 v[74:77], v[12:13], off offset:176
	global_load_dwordx4 v[78:81], v[14:15], off offset:176
	v_cvt_pk_bf16_f32 v50, v50, v51
	v_cvt_pk_bf16_f32 v51, v52, v53
	s_waitcnt vmcnt(0)
	v_pk_fma_f32 v[74:75], v[82:83], v[74:75], v[78:79]
	v_pk_fma_f32 v[76:77], v[84:85], v[76:77], v[80:81]
	v_cvt_pk_bf16_f32 v52, v74, v75
	v_cvt_pk_bf16_f32 v53, v76, v77
	global_store_dwordx4 v[32:33], v[74:77], off offset:176
	global_store_dwordx4 v[48:49], v[50:53], off offset:80
	global_load_dwordx4 v[50:53], v[12:13], off offset:256
	s_nop 0
	global_load_dwordx4 v[74:77], v[14:15], off offset:256
	v_pk_add_f32 v[78:79], v[132:133], v[0:1] op_sel_hi:[1,0] neg_lo:[0,1] neg_hi:[0,1]
	v_pk_add_f32 v[80:81], v[142:143], v[0:1] op_sel_hi:[1,0] neg_lo:[0,1] neg_hi:[0,1]
	v_pk_mul_f32 v[78:79], v[78:79], v[30:31] op_sel_hi:[1,0]
	v_pk_mul_f32 v[80:81], v[80:81], v[30:31] op_sel_hi:[1,0]
	v_pk_add_f32 v[82:83], v[126:127], v[0:1] op_sel_hi:[1,0] neg_lo:[0,1] neg_hi:[0,1]
	v_pk_add_f32 v[84:85], v[136:137], v[0:1] op_sel_hi:[1,0] neg_lo:[0,1] neg_hi:[0,1]
	v_pk_mul_f32 v[82:83], v[82:83], v[30:31] op_sel_hi:[1,0]
	v_pk_mul_f32 v[84:85], v[84:85], v[30:31] op_sel_hi:[1,0]
	s_waitcnt vmcnt(0)
	v_pk_fma_f32 v[50:51], v[78:79], v[50:51], v[74:75]
	v_pk_fma_f32 v[52:53], v[80:81], v[52:53], v[76:77]
	global_store_dwordx4 v[32:33], v[50:53], off offset:256
	global_load_dwordx4 v[74:77], v[12:13], off offset:272
	global_load_dwordx4 v[78:81], v[14:15], off offset:272
	v_cvt_pk_bf16_f32 v50, v50, v51
	v_cvt_pk_bf16_f32 v51, v52, v53
	s_waitcnt vmcnt(0)
	v_pk_fma_f32 v[74:75], v[82:83], v[74:75], v[78:79]
	v_pk_fma_f32 v[76:77], v[84:85], v[76:77], v[80:81]
	v_cvt_pk_bf16_f32 v52, v74, v75
	v_cvt_pk_bf16_f32 v53, v76, v77
	global_store_dwordx4 v[32:33], v[74:77], off offset:272
	global_store_dwordx4 v[48:49], v[50:53], off offset:128
	global_load_dwordx4 v[50:53], v[12:13], off offset:288
	s_nop 0
	global_load_dwordx4 v[74:77], v[14:15], off offset:288
	v_pk_add_f32 v[78:79], v[112:113], v[0:1] op_sel_hi:[1,0] neg_lo:[0,1] neg_hi:[0,1]
	v_pk_add_f32 v[80:81], v[128:129], v[0:1] op_sel_hi:[1,0] neg_lo:[0,1] neg_hi:[0,1]
	v_pk_mul_f32 v[78:79], v[78:79], v[30:31] op_sel_hi:[1,0]
	v_pk_mul_f32 v[80:81], v[80:81], v[30:31] op_sel_hi:[1,0]
	v_pk_add_f32 v[82:83], v[106:107], v[0:1] op_sel_hi:[1,0] neg_lo:[0,1] neg_hi:[0,1]
	v_pk_add_f32 v[84:85], v[118:119], v[0:1] op_sel_hi:[1,0] neg_lo:[0,1] neg_hi:[0,1]
	v_pk_mul_f32 v[82:83], v[82:83], v[30:31] op_sel_hi:[1,0]
	v_pk_mul_f32 v[84:85], v[84:85], v[30:31] op_sel_hi:[1,0]
	s_waitcnt vmcnt(0)
	v_pk_fma_f32 v[50:51], v[78:79], v[50:51], v[74:75]
	v_pk_fma_f32 v[52:53], v[80:81], v[52:53], v[76:77]
	global_store_dwordx4 v[32:33], v[50:53], off offset:288
	global_load_dwordx4 v[74:77], v[12:13], off offset:304
	global_load_dwordx4 v[78:81], v[14:15], off offset:304
	v_cvt_pk_bf16_f32 v50, v50, v51
	v_cvt_pk_bf16_f32 v51, v52, v53
	s_waitcnt vmcnt(0)
	v_pk_fma_f32 v[74:75], v[82:83], v[74:75], v[78:79]
	v_pk_fma_f32 v[76:77], v[84:85], v[76:77], v[80:81]
	v_cvt_pk_bf16_f32 v52, v74, v75
	v_cvt_pk_bf16_f32 v53, v76, v77
	global_store_dwordx4 v[32:33], v[74:77], off offset:304
	global_store_dwordx4 v[48:49], v[50:53], off offset:144
	global_load_dwordx4 v[50:53], v[12:13], off offset:384
	s_nop 0
	global_load_dwordx4 v[74:77], v[14:15], off offset:384
	v_pk_add_f32 v[78:79], v[104:105], v[0:1] op_sel_hi:[1,0] neg_lo:[0,1] neg_hi:[0,1]
	v_pk_add_f32 v[80:81], v[122:123], v[0:1] op_sel_hi:[1,0] neg_lo:[0,1] neg_hi:[0,1]
	v_pk_mul_f32 v[78:79], v[78:79], v[30:31] op_sel_hi:[1,0]
	v_pk_mul_f32 v[80:81], v[80:81], v[30:31] op_sel_hi:[1,0]
	v_pk_add_f32 v[82:83], v[102:103], v[0:1] op_sel_hi:[1,0] neg_lo:[0,1] neg_hi:[0,1]
	v_pk_add_f32 v[84:85], v[120:121], v[0:1] op_sel_hi:[1,0] neg_lo:[0,1] neg_hi:[0,1]
	v_pk_mul_f32 v[82:83], v[82:83], v[30:31] op_sel_hi:[1,0]
	v_pk_mul_f32 v[84:85], v[84:85], v[30:31] op_sel_hi:[1,0]
	s_waitcnt vmcnt(0)
	v_pk_fma_f32 v[50:51], v[78:79], v[50:51], v[74:75]
	v_pk_fma_f32 v[52:53], v[80:81], v[52:53], v[76:77]
	global_store_dwordx4 v[32:33], v[50:53], off offset:384
	global_load_dwordx4 v[74:77], v[12:13], off offset:400
	global_load_dwordx4 v[78:81], v[14:15], off offset:400
	v_cvt_pk_bf16_f32 v50, v50, v51
	v_cvt_pk_bf16_f32 v51, v52, v53
	s_waitcnt vmcnt(0)
; #define GAS __attribute__((address_space(1)))
; DI unsigned pk2(float lo, float hi) { f32x2 v = {lo, hi}; bf16x2v b = __builtin_convertvector(v, bf16x2v); return __builtin_bit_cast(unsigned, b); }
;   DI void full(const int mt_, const int nt_, f32x16 (&acc)[2][2][2], const int tw, const int fw, const int r, const int hh, char* lds, const int tid) const {
;     ...
; #pragma unroll
;     for (int mt = 0; mt < 2; ++mt) {
;       const int tl = tw * 64 + mt * 32 + r;
;       float S = 0.f, Q = 0.f;
; #pragma unroll
;       for (int k = 0; k < 4; ++k) {
;         const unsigned long long pk = __hip_atomic_load((GAS unsigned long long*)(xchg + ((size_t)(mt_ * 4 + k) * 256 + tl) * 2), __ATOMIC_RELAXED, __HIP_MEMORY_SCOPE_AGENT);
;         S += __uint_as_float((unsigned)pk);
;         Q += __uint_as_float((unsigned)(pk >> 32));
;       }
;       const float mean = S * (1.f / 1024.f);
;       const float rstd = rsqrtf(fmaxf(Q * (1.f / 1024.f) - mean * mean, 0.f) + 1e-5f);
;       const int c0 = nt_ * 256 + fw * 128 + 16 * hh;
;       const size_t rowo = (size_t)(mt_ * 256 + tl) * 1024 + c0;
; #pragma unroll
;       for (int half = 0; half < 2; ++half)
; #pragma unroll
;         for (int nt = 0; nt < 2; ++nt) {
; #pragma unroll
;           for (int gp = 0; gp < 2; ++gp) {
;             const int co = half * 64 + nt * 32 + 8 * gp;
;             u32x4 ob;
; #pragma unroll
;             for (int h2 = 0; h2 < 2; ++h2) {
;               f32x4 gv = *(const f32x4*)(g + c0 + co + 4 * h2), bv = *(const f32x4*)(b + c0 + co + 4 * h2), o;
; #pragma unroll
;               for (int jj = 0; jj < 4; ++jj) o[jj] = (acc[half][nt][mt][8 * gp + 4 * h2 + jj] - mean) * rstd * gv[jj] + bv[jj];
;               *(f32x4*)(xout + rowo + co + 4 * h2) = o;
;               ob[2 * h2] = pk2(o[0], o[1]); ob[2 * h2 + 1] = pk2(o[2], o[3]);
;             }
;             *(u32x4*)(xb + rowo + co) = ob;
;           }
;           __builtin_amdgcn_sched_barrier(0);
;         }
	v_pk_fma_f32 v[74:75], v[82:83], v[74:75], v[78:79]
	v_pk_fma_f32 v[76:77], v[84:85], v[76:77], v[80:81]
	v_cvt_pk_bf16_f32 v52, v74, v75
	v_cvt_pk_bf16_f32 v53, v76, v77
	global_store_dwordx4 v[32:33], v[74:77], off offset:400
	global_store_dwordx4 v[48:49], v[50:53], off offset:192
	global_load_dwordx4 v[50:53], v[12:13], off offset:416
	s_nop 0
	global_load_dwordx4 v[74:77], v[14:15], off offset:416
	v_pk_add_f32 v[78:79], v[94:95], v[0:1] op_sel_hi:[1,0] neg_lo:[0,1] neg_hi:[0,1]
	v_pk_add_f32 v[80:81], v[108:109], v[0:1] op_sel_hi:[1,0] neg_lo:[0,1] neg_hi:[0,1]
	v_pk_mul_f32 v[78:79], v[78:79], v[30:31] op_sel_hi:[1,0]
	v_pk_mul_f32 v[80:81], v[80:81], v[30:31] op_sel_hi:[1,0]
	v_pk_add_f32 v[82:83], v[96:97], v[0:1] op_sel_hi:[1,0] neg_lo:[0,1] neg_hi:[0,1]
	v_pk_add_f32 v[84:85], v[110:111], v[0:1] op_sel_hi:[1,0] neg_lo:[0,1] neg_hi:[0,1]
	v_pk_mul_f32 v[82:83], v[82:83], v[30:31] op_sel_hi:[1,0]
	v_pk_mul_f32 v[84:85], v[84:85], v[30:31] op_sel_hi:[1,0]
	s_waitcnt vmcnt(0)
	v_pk_fma_f32 v[50:51], v[78:79], v[50:51], v[74:75]
	v_pk_fma_f32 v[52:53], v[80:81], v[52:53], v[76:77]
	global_store_dwordx4 v[32:33], v[50:53], off offset:416
	global_load_dwordx4 v[74:77], v[12:13], off offset:432
	global_load_dwordx4 v[78:81], v[14:15], off offset:432
	v_cvt_pk_bf16_f32 v30, v50, v51
	v_cvt_pk_bf16_f32 v31, v52, v53
	s_waitcnt vmcnt(0)
	v_pk_fma_f32 v[50:51], v[82:83], v[74:75], v[78:79]
	v_pk_fma_f32 v[52:53], v[84:85], v[76:77], v[80:81]
	global_store_dwordx4 v[32:33], v[50:53], off offset:432
	v_cvt_pk_bf16_f32 v32, v50, v51
	v_cvt_pk_bf16_f32 v33, v52, v53
	global_store_dwordx4 v[48:49], v[30:33], off offset:208
	v_or_b32_e32 v0, 32, v223
	s_nop 0
	v_lshlrev_b32_e32 v32, 3, v0
	global_load_dwordx2 v[78:79], v32, s[20:21] sc1
	v_or_b32_e32 v0, s4, v0
	global_load_dwordx2 v[80:81], v32, s[22:23] sc1
	global_load_dwordx2 v[30:31], v32, s[26:27] sc1
	global_load_dwordx2 v[32:33], v32, s[24:25] sc1
	global_load_dwordx4 v[50:53], v[12:13], off
	global_load_dwordx4 v[74:77], v[14:15], off
	s_waitcnt vmcnt(2)
	v_add_f32_e32 v48, 0, v79
	v_add_f32_e32 v48, v48, v81
	v_add_f32_e32 v48, v48, v33
	v_add_f32_e32 v33, 0, v78
	v_add_f32_e32 v33, v33, v80
	v_add_f32_e32 v33, v33, v32
	v_add_f32_e32 v30, v33, v30
	v_mul_f32_e32 v30, 0x3a800000, v30
	v_add_f32_e32 v31, v48, v31
	v_mul_f32_e32 v32, v30, v30
	v_fma_f32 v31, v31, s67, -v32
	v_max_f32_e32 v31, 0, v31
	v_add_f32_e32 v31, 0x3727c5ac, v31
	v_cmp_gt_f32_e32 vcc, s63, v31
	v_mul_f32_e32 v32, 0x4b800000, v31
	v_lshlrev_b64 v[48:49], 10, v[0:1]
	v_cndmask_b32_e32 v31, v31, v32, vcc
	v_rsq_f32_e32 v31, v31
	v_lshl_add_u64 v[48:49], v[48:49], 0, v[16:17]
	v_mul_f32_e32 v32, 0x45800000, v31
	v_cndmask_b32_e32 v32, v31, v32, vcc
	v_pk_add_f32 v[16:17], v[90:91], v[30:31] op_sel_hi:[1,0] neg_lo:[0,1] neg_hi:[0,1]
	v_pk_add_f32 v[70:71], v[70:71], v[30:31] op_sel_hi:[1,0] neg_lo:[0,1] neg_hi:[0,1]
	v_pk_mul_f32 v[16:17], v[16:17], v[32:33] op_sel_hi:[1,0]
	v_pk_mul_f32 v[70:71], v[70:71], v[32:33] op_sel_hi:[1,0]
	s_waitcnt vmcnt(0)
	v_pk_fma_f32 v[50:51], v[50:51], v[16:17], v[74:75]
	v_pk_add_f32 v[16:17], v[92:93], v[30:31] op_sel_hi:[1,0] neg_lo:[0,1] neg_hi:[0,1]
	s_nop 0
	v_pk_mul_f32 v[16:17], v[16:17], v[32:33] op_sel_hi:[1,0]
	s_nop 0
	v_pk_fma_f32 v[52:53], v[52:53], v[16:17], v[76:77]
	v_lshl_add_u64 v[16:17], v[48:49], 2, s[8:9]
	global_store_dwordx4 v[16:17], v[50:53], off
	global_load_dwordx4 v[74:77], v[12:13], off offset:16
	global_load_dwordx4 v[78:81], v[14:15], off offset:16
	v_cvt_pk_bf16_f32 v50, v50, v51
	v_cvt_pk_bf16_f32 v51, v52, v53
	v_pk_add_f32 v[52:53], v[86:87], v[30:31] op_sel_hi:[1,0] neg_lo:[0,1] neg_hi:[0,1]
	v_lshl_add_u64 v[48:49], v[48:49], 1, s[12:13]
	v_pk_mul_f32 v[52:53], v[52:53], v[32:33] op_sel_hi:[1,0]
	s_waitcnt vmcnt(0)
	v_pk_fma_f32 v[74:75], v[74:75], v[52:53], v[78:79]
	v_pk_add_f32 v[52:53], v[88:89], v[30:31] op_sel_hi:[1,0] neg_lo:[0,1] neg_hi:[0,1]
	s_nop 0
	v_pk_mul_f32 v[52:53], v[52:53], v[32:33] op_sel_hi:[1,0]
	s_nop 0
	v_pk_fma_f32 v[76:77], v[76:77], v[52:53], v[80:81]
	v_cvt_pk_bf16_f32 v52, v74, v75
	v_cvt_pk_bf16_f32 v53, v76, v77
	global_store_dwordx4 v[16:17], v[74:77], off offset:16
	global_store_dwordx4 v[48:49], v[50:53], off
	global_load_dwordx4 v[50:53], v[12:13], off offset:32
	s_nop 0
	global_load_dwordx4 v[74:77], v[14:15], off offset:32
	s_waitcnt vmcnt(0)
	v_pk_fma_f32 v[50:51], v[50:51], v[70:71], v[74:75]
	v_pk_add_f32 v[70:71], v[72:73], v[30:31] op_sel_hi:[1,0] neg_lo:[0,1] neg_hi:[0,1]
	s_nop 0
	v_pk_mul_f32 v[70:71], v[70:71], v[32:33] op_sel_hi:[1,0]
	s_nop 0
	v_pk_fma_f32 v[52:53], v[52:53], v[70:71], v[76:77]
	global_store_dwordx4 v[16:17], v[50:53], off offset:32
	global_load_dwordx4 v[70:73], v[12:13], off offset:48
	global_load_dwordx4 v[74:77], v[14:15], off offset:48
	v_cvt_pk_bf16_f32 v50, v50, v51
	v_cvt_pk_bf16_f32 v51, v52, v53
	v_pk_add_f32 v[52:53], v[68:69], v[30:31] op_sel_hi:[1,0] neg_lo:[0,1] neg_hi:[0,1]
	s_nop 0
	v_pk_mul_f32 v[52:53], v[52:53], v[32:33] op_sel_hi:[1,0]
	s_waitcnt vmcnt(0)
; DI unsigned pk2(float lo, float hi) { f32x2 v = {lo, hi}; bf16x2v b = __builtin_convertvector(v, bf16x2v); return __builtin_bit_cast(unsigned, b); }
;   DI void full(const int mt_, const int nt_, f32x16 (&acc)[2][2][2], const int tw, const int fw, const int r, const int hh, char* lds, const int tid) const {
;     ...
; #pragma unroll
;       for (int half = 0; half < 2; ++half)
; #pragma unroll
;         for (int nt = 0; nt < 2; ++nt) {
; #pragma unroll
;           for (int gp = 0; gp < 2; ++gp) {
;             const int co = half * 64 + nt * 32 + 8 * gp;
;             u32x4 ob;
; #pragma unroll
;             for (int h2 = 0; h2 < 2; ++h2) {
;               f32x4 gv = *(const f32x4*)(g + c0 + co + 4 * h2), bv = *(const f32x4*)(b + c0 + co + 4 * h2), o;
; #pragma unroll
;               for (int jj = 0; jj < 4; ++jj) o[jj] = (acc[half][nt][mt][8 * gp + 4 * h2 + jj] - mean) * rstd * gv[jj] + bv[jj];
;               *(f32x4*)(xout + rowo + co + 4 * h2) = o;
;               ob[2 * h2] = pk2(o[0], o[1]); ob[2 * h2 + 1] = pk2(o[2], o[3]);
;             }
;             *(u32x4*)(xb + rowo + co) = ob;
;           }
;           __builtin_amdgcn_sched_barrier(0);
;         }
	v_pk_fma_f32 v[68:69], v[70:71], v[52:53], v[74:75]
	v_pk_add_f32 v[52:53], v[66:67], v[30:31] op_sel_hi:[1,0] neg_lo:[0,1] neg_hi:[0,1]
	s_nop 0
	v_pk_mul_f32 v[52:53], v[52:53], v[32:33] op_sel_hi:[1,0]
	s_nop 0
	v_pk_fma_f32 v[70:71], v[72:73], v[52:53], v[76:77]
	v_cvt_pk_bf16_f32 v52, v68, v69
	v_cvt_pk_bf16_f32 v53, v70, v71
	global_store_dwordx4 v[16:17], v[68:71], off offset:48
	global_store_dwordx4 v[48:49], v[50:53], off offset:16
	global_load_dwordx4 v[50:53], v[12:13], off offset:128
	s_nop 0
	global_load_dwordx4 v[66:69], v[14:15], off offset:128
	v_pk_add_f32 v[60:61], v[60:61], v[30:31] op_sel_hi:[1,0] neg_lo:[0,1] neg_hi:[0,1]
	v_pk_add_f32 v[64:65], v[64:65], v[30:31] op_sel_hi:[1,0] neg_lo:[0,1] neg_hi:[0,1]
	v_pk_mul_f32 v[60:61], v[60:61], v[32:33] op_sel_hi:[1,0]
	v_pk_mul_f32 v[64:65], v[64:65], v[32:33] op_sel_hi:[1,0]
	v_pk_add_f32 v[56:57], v[56:57], v[30:31] op_sel_hi:[1,0] neg_lo:[0,1] neg_hi:[0,1]
	v_pk_add_f32 v[54:55], v[54:55], v[30:31] op_sel_hi:[1,0] neg_lo:[0,1] neg_hi:[0,1]
	v_pk_mul_f32 v[56:57], v[56:57], v[32:33] op_sel_hi:[1,0]
	v_pk_mul_f32 v[54:55], v[54:55], v[32:33] op_sel_hi:[1,0]
	v_pk_add_f32 v[44:45], v[44:45], v[30:31] op_sel_hi:[1,0] neg_lo:[0,1] neg_hi:[0,1]
	v_pk_add_f32 v[46:47], v[46:47], v[30:31] op_sel_hi:[1,0] neg_lo:[0,1] neg_hi:[0,1]
	s_waitcnt vmcnt(0)
	v_pk_fma_f32 v[50:51], v[60:61], v[50:51], v[66:67]
	v_pk_fma_f32 v[52:53], v[64:65], v[52:53], v[68:69]
	global_store_dwordx4 v[16:17], v[50:53], off offset:128
	global_load_dwordx4 v[64:67], v[12:13], off offset:144
	global_load_dwordx4 v[68:71], v[14:15], off offset:144
	v_pk_add_f32 v[60:61], v[62:63], v[30:31] op_sel_hi:[1,0] neg_lo:[0,1] neg_hi:[0,1]
	v_cvt_pk_bf16_f32 v50, v50, v51
	v_pk_mul_f32 v[62:63], v[60:61], v[32:33] op_sel_hi:[1,0]
	v_cvt_pk_bf16_f32 v51, v52, v53
	v_pk_mul_f32 v[46:47], v[46:47], v[32:33] op_sel_hi:[1,0]
	s_waitcnt vmcnt(0)
	v_pk_fma_f32 v[60:61], v[56:57], v[64:65], v[68:69]
	v_pk_fma_f32 v[62:63], v[62:63], v[66:67], v[70:71]
	v_cvt_pk_bf16_f32 v52, v60, v61
	v_cvt_pk_bf16_f32 v53, v62, v63
	global_store_dwordx4 v[16:17], v[60:63], off offset:144
	global_store_dwordx4 v[48:49], v[50:53], off offset:64
	global_load_dwordx4 v[50:53], v[12:13], off offset:160
	s_nop 0
	global_load_dwordx4 v[60:63], v[14:15], off offset:160
	v_pk_add_f32 v[56:57], v[58:59], v[30:31] op_sel_hi:[1,0] neg_lo:[0,1] neg_hi:[0,1]
	s_waitcnt vmcnt(0)
	v_pk_fma_f32 v[50:51], v[54:55], v[50:51], v[60:61]
	v_pk_mul_f32 v[56:57], v[56:57], v[32:33] op_sel_hi:[1,0]
	s_nop 0
	v_pk_fma_f32 v[52:53], v[56:57], v[52:53], v[62:63]
	global_store_dwordx4 v[16:17], v[50:53], off offset:160
	global_load_dwordx4 v[54:57], v[12:13], off offset:176
	global_load_dwordx4 v[58:61], v[14:15], off offset:176
	v_pk_mul_f32 v[62:63], v[44:45], v[32:33] op_sel_hi:[1,0]
	v_cvt_pk_bf16_f32 v44, v50, v51
	v_cvt_pk_bf16_f32 v45, v52, v53
	s_waitcnt vmcnt(0)
	v_pk_fma_f32 v[50:51], v[62:63], v[54:55], v[58:59]
	v_pk_fma_f32 v[52:53], v[46:47], v[56:57], v[60:61]
	v_cvt_pk_bf16_f32 v46, v50, v51
	v_cvt_pk_bf16_f32 v47, v52, v53
	global_store_dwordx4 v[16:17], v[50:53], off offset:176
	global_store_dwordx4 v[48:49], v[44:47], off offset:80
	global_load_dwordx4 v[44:47], v[12:13], off offset:256
	s_nop 0
	global_load_dwordx4 v[50:53], v[14:15], off offset:256
	v_pk_add_f32 v[38:39], v[38:39], v[30:31] op_sel_hi:[1,0] neg_lo:[0,1] neg_hi:[0,1]
	v_pk_add_f32 v[42:43], v[42:43], v[30:31] op_sel_hi:[1,0] neg_lo:[0,1] neg_hi:[0,1]
	v_pk_mul_f32 v[38:39], v[38:39], v[32:33] op_sel_hi:[1,0]
	v_pk_mul_f32 v[54:55], v[42:43], v[32:33] op_sel_hi:[1,0]
	v_pk_add_f32 v[34:35], v[34:35], v[30:31] op_sel_hi:[1,0] neg_lo:[0,1] neg_hi:[0,1]
	v_pk_add_f32 v[26:27], v[26:27], v[30:31] op_sel_hi:[1,0] neg_lo:[0,1] neg_hi:[0,1]
	v_pk_mul_f32 v[34:35], v[34:35], v[32:33] op_sel_hi:[1,0]
	v_pk_mul_f32 v[26:27], v[26:27], v[32:33] op_sel_hi:[1,0]
	v_pk_add_f32 v[24:25], v[24:25], v[30:31] op_sel_hi:[1,0] neg_lo:[0,1] neg_hi:[0,1]
	s_waitcnt vmcnt(0)
	v_pk_fma_f32 v[42:43], v[38:39], v[44:45], v[50:51]
	v_pk_fma_f32 v[44:45], v[54:55], v[46:47], v[52:53]
	global_store_dwordx4 v[16:17], v[42:45], off offset:256
	global_load_dwordx4 v[50:53], v[12:13], off offset:272
	global_load_dwordx4 v[54:57], v[14:15], off offset:272
	v_pk_add_f32 v[38:39], v[40:41], v[30:31] op_sel_hi:[1,0] neg_lo:[0,1] neg_hi:[0,1]
	s_waitcnt vmcnt(0)
; DI unsigned pk2(float lo, float hi) { f32x2 v = {lo, hi}; bf16x2v b = __builtin_convertvector(v, bf16x2v); return __builtin_bit_cast(unsigned, b); }
; template <class Epi>
; DI void gemm_phase(const bf16_t* __restrict__ X, const int ldx, const bf16_t* __restrict__ Wt, const int N, const int K, const Epi& epi, char* lds) {
;     ...
;   for (int chunk = xcd; chunk < nchunks; chunk += 8) {
;   DI void full(const int mt_, const int nt_, f32x16 (&acc)[2][2][2], const int tw, const int fw, const int r, const int hh, char* lds, const int tid) const {
;     ...
; #pragma unroll
;       for (int half = 0; half < 2; ++half)
; #pragma unroll
;         for (int nt = 0; nt < 2; ++nt) {
; #pragma unroll
;           for (int gp = 0; gp < 2; ++gp) {
;             const int co = half * 64 + nt * 32 + 8 * gp;
;             u32x4 ob;
; #pragma unroll
;             for (int h2 = 0; h2 < 2; ++h2) {
;               f32x4 gv = *(const f32x4*)(g + c0 + co + 4 * h2), bv = *(const f32x4*)(b + c0 + co + 4 * h2), o;
; #pragma unroll
;               for (int jj = 0; jj < 4; ++jj) o[jj] = (acc[half][nt][mt][8 * gp + 4 * h2 + jj] - mean) * rstd * gv[jj] + bv[jj];
;               *(f32x4*)(xout + rowo + co + 4 * h2) = o;
;               ob[2 * h2] = pk2(o[0], o[1]); ob[2 * h2 + 1] = pk2(o[2], o[3]);
;             }
;             *(u32x4*)(xb + rowo + co) = ob;
;           }
;           __builtin_amdgcn_sched_barrier(0);
;         }
;     }
;     __syncthreads();
	v_pk_fma_f32 v[40:41], v[34:35], v[50:51], v[54:55]
	v_pk_mul_f32 v[46:47], v[38:39], v[32:33] op_sel_hi:[1,0]
	v_cvt_pk_bf16_f32 v38, v42, v43
	v_pk_fma_f32 v[42:43], v[46:47], v[52:53], v[56:57]
	v_cvt_pk_bf16_f32 v39, v44, v45
	global_store_dwordx4 v[16:17], v[40:43], off offset:272
	v_pk_add_f32 v[34:35], v[36:37], v[30:31] op_sel_hi:[1,0] neg_lo:[0,1] neg_hi:[0,1]
	s_nop 0
	v_cvt_pk_bf16_f32 v40, v40, v41
	v_cvt_pk_bf16_f32 v41, v42, v43
	global_store_dwordx4 v[48:49], v[38:41], off offset:128
	global_load_dwordx4 v[38:41], v[12:13], off offset:288
	s_nop 0
	global_load_dwordx4 v[42:45], v[14:15], off offset:288
	v_pk_mul_f32 v[36:37], v[34:35], v[32:33] op_sel_hi:[1,0]
	s_waitcnt vmcnt(0)
	v_pk_fma_f32 v[34:35], v[26:27], v[38:39], v[42:43]
	v_pk_fma_f32 v[36:37], v[36:37], v[40:41], v[44:45]
	global_store_dwordx4 v[16:17], v[34:37], off offset:288
	global_load_dwordx4 v[38:41], v[12:13], off offset:304
	global_load_dwordx4 v[42:45], v[14:15], off offset:304
	v_pk_add_f32 v[26:27], v[28:29], v[30:31] op_sel_hi:[1,0] neg_lo:[0,1] neg_hi:[0,1]
	v_pk_mul_f32 v[28:29], v[24:25], v[32:33] op_sel_hi:[1,0]
	v_pk_mul_f32 v[46:47], v[26:27], v[32:33] op_sel_hi:[1,0]
	v_cvt_pk_bf16_f32 v24, v34, v35
	v_cvt_pk_bf16_f32 v25, v36, v37
	s_waitcnt vmcnt(0)
	v_pk_fma_f32 v[26:27], v[28:29], v[38:39], v[42:43]
	v_pk_fma_f32 v[28:29], v[46:47], v[40:41], v[44:45]
	global_store_dwordx4 v[16:17], v[26:29], off offset:304
	s_nop 1
	v_cvt_pk_bf16_f32 v26, v26, v27
	v_cvt_pk_bf16_f32 v27, v28, v29
	global_store_dwordx4 v[48:49], v[24:27], off offset:144
	global_load_dwordx4 v[24:27], v[12:13], off offset:384
	s_nop 0
	global_load_dwordx4 v[34:37], v[14:15], off offset:384
	v_pk_add_f32 v[18:19], v[18:19], v[30:31] op_sel_hi:[1,0] neg_lo:[0,1] neg_hi:[0,1]
	v_pk_add_f32 v[22:23], v[22:23], v[30:31] op_sel_hi:[1,0] neg_lo:[0,1] neg_hi:[0,1]
	v_pk_mul_f32 v[18:19], v[18:19], v[32:33] op_sel_hi:[1,0]
	v_pk_mul_f32 v[28:29], v[22:23], v[32:33] op_sel_hi:[1,0]
	v_pk_add_f32 v[6:7], v[6:7], v[30:31] op_sel_hi:[1,0] neg_lo:[0,1] neg_hi:[0,1]
	v_pk_add_f32 v[2:3], v[2:3], v[30:31] op_sel_hi:[1,0] neg_lo:[0,1] neg_hi:[0,1]
	v_pk_mul_f32 v[6:7], v[6:7], v[32:33] op_sel_hi:[1,0]
	v_pk_mul_f32 v[2:3], v[2:3], v[32:33] op_sel_hi:[1,0]
	s_waitcnt vmcnt(0)
	v_pk_fma_f32 v[22:23], v[18:19], v[24:25], v[34:35]
	v_pk_fma_f32 v[24:25], v[28:29], v[26:27], v[36:37]
	global_store_dwordx4 v[16:17], v[22:25], off offset:384
	global_load_dwordx4 v[26:29], v[12:13], off offset:400
	global_load_dwordx4 v[34:37], v[14:15], off offset:400
	v_pk_add_f32 v[18:19], v[20:21], v[30:31] op_sel_hi:[1,0] neg_lo:[0,1] neg_hi:[0,1]
	s_waitcnt vmcnt(0)
	v_pk_fma_f32 v[20:21], v[6:7], v[26:27], v[34:35]
	v_pk_mul_f32 v[38:39], v[18:19], v[32:33] op_sel_hi:[1,0]
	v_cvt_pk_bf16_f32 v18, v22, v23
	v_pk_fma_f32 v[22:23], v[38:39], v[28:29], v[36:37]
	v_cvt_pk_bf16_f32 v19, v24, v25
	global_store_dwordx4 v[16:17], v[20:23], off offset:400
	v_pk_add_f32 v[6:7], v[8:9], v[30:31] op_sel_hi:[1,0] neg_lo:[0,1] neg_hi:[0,1]
	s_nop 0
	v_cvt_pk_bf16_f32 v20, v20, v21
	v_cvt_pk_bf16_f32 v21, v22, v23
	global_store_dwordx4 v[48:49], v[18:21], off offset:192
	global_load_dwordx4 v[18:21], v[12:13], off offset:416
	s_nop 0
	global_load_dwordx4 v[22:25], v[14:15], off offset:416
	v_pk_mul_f32 v[8:9], v[6:7], v[32:33] op_sel_hi:[1,0]
	s_waitcnt vmcnt(0)
	v_pk_fma_f32 v[6:7], v[2:3], v[18:19], v[22:23]
	v_pk_fma_f32 v[8:9], v[8:9], v[20:21], v[24:25]
	global_store_dwordx4 v[16:17], v[6:9], off offset:416
	global_load_dwordx4 v[18:21], v[12:13], off offset:432
	s_nop 0
	global_load_dwordx4 v[12:15], v[14:15], off offset:432
	v_pk_add_f32 v[2:3], v[4:5], v[30:31] op_sel_hi:[1,0] neg_lo:[0,1] neg_hi:[0,1]
	v_pk_add_f32 v[4:5], v[10:11], v[30:31] op_sel_hi:[1,0] neg_lo:[0,1] neg_hi:[0,1]
	v_pk_mul_f32 v[10:11], v[2:3], v[32:33] op_sel_hi:[1,0]
	v_pk_mul_f32 v[22:23], v[4:5], v[32:33] op_sel_hi:[1,0]
	v_cvt_pk_bf16_f32 v2, v6, v7
	v_cvt_pk_bf16_f32 v3, v8, v9
	s_waitcnt vmcnt(0)
	v_pk_fma_f32 v[4:5], v[10:11], v[18:19], v[12:13]
	v_pk_fma_f32 v[6:7], v[22:23], v[20:21], v[14:15]
	global_store_dwordx4 v[16:17], v[4:7], off offset:432
	s_nop 1
	v_cvt_pk_bf16_f32 v4, v4, v5
	v_cvt_pk_bf16_f32 v5, v6, v7
	global_store_dwordx4 v[48:49], v[2:5], off offset:208
	s_barrier
	s_add_i32 s2, s34, 8
	s_cmp_gt_u32 s34, 7
	s_mov_b32 s34, s2
	s_cbranch_scc1 .LBB0_279

; #define GAS __attribute__((address_space(1)))
; DI unsigned pk2(float lo, float hi) { f32x2 v = {lo, hi}; bf16x2v b = __builtin_convertvector(v, bf16x2v); return __builtin_bit_cast(unsigned, b); }
;   DI void full(const int mt_, const int nt_, f32x16 (&acc)[2][2][2], const int tw, const int fw, const int r, const int hh, char* lds, const int tid) const {
;     ...
; #pragma unroll
;     for (int mt = 0; mt < 2; ++mt) {
;       const int tl = tw * 64 + mt * 32 + r;
;       float S = 0.f, Q = 0.f;
; #pragma unroll
;       for (int k = 0; k < 4; ++k) {
;         const unsigned long long pk = __hip_atomic_load((GAS unsigned long long*)(xchg + ((size_t)(mt_ * 4 + k) * 256 + tl) * 2), __ATOMIC_RELAXED, __HIP_MEMORY_SCOPE_AGENT);
;         S += __uint_as_float((unsigned)pk);
;         Q += __uint_as_float((unsigned)(pk >> 32));
;       }
;       const float mean = S * (1.f / 1024.f);
;       const float rstd = rsqrtf(fmaxf(Q * (1.f / 1024.f) - mean * mean, 0.f) + 1e-5f);
;       const int c0 = nt_ * 256 + fw * 128 + 16 * hh;
;       const size_t rowo = (size_t)(mt_ * 256 + tl) * 1024 + c0;
; #pragma unroll
;       for (int half = 0; half < 2; ++half)
; #pragma unroll
;         for (int nt = 0; nt < 2; ++nt) {
; #pragma unroll
;           for (int gp = 0; gp < 2; ++gp) {
;             const int co = half * 64 + nt * 32 + 8 * gp;
;             u32x4 ob;
; #pragma unroll
;             for (int h2 = 0; h2 < 2; ++h2) {
;               f32x4 gv = *(const f32x4*)(g + c0 + co + 4 * h2), bv = *(const f32x4*)(b + c0 + co + 4 * h2), o;
; #pragma unroll
;               for (int jj = 0; jj < 4; ++jj) o[jj] = (acc[half][nt][mt][8 * gp + 4 * h2 + jj] - mean) * rstd * gv[jj] + bv[jj];
;               *(f32x4*)(xout + rowo + co + 4 * h2) = o;
;               ob[2 * h2] = pk2(o[0], o[1]); ob[2 * h2 + 1] = pk2(o[2], o[3]);
;             }
;             *(u32x4*)(xb + rowo + co) = ob;
;           }
;           __builtin_amdgcn_sched_barrier(0);
;         }
.LBB0_699:
	s_or_b64 exec, exec, s[18:19]
	s_lshl_b32 s96, s2, 2
	s_lshl_b64 s[2:3], s[96:97], 11
	v_lshlrev_b64 v[12:13], 10, v[0:1]
	v_lshlrev_b32_e32 v0, 4, v224
	v_add_u32_e32 v14, s48, v182
	s_add_u32 s18, s27, s2
	v_or_b32_e32 v16, v0, v14
	s_addc_u32 s19, s28, s3
	v_lshlrev_b32_e32 v0, 3, v223
	s_barrier
	global_load_dwordx2 v[32:33], v0, s[18:19] sc1
	s_or_b32 s2, s96, 1
	s_mov_b32 s3, s97
	s_lshl_b64 s[2:3], s[2:3], 11
	s_add_u32 s20, s27, s2
	s_addc_u32 s21, s28, s3
	s_or_b32 s2, s96, 2
	s_mov_b32 s3, s97
	s_lshl_b64 s[2:3], s[2:3], 11
	s_add_u32 s22, s27, s2
	s_addc_u32 s23, s28, s3
	s_or_b32 s96, s96, 3
	s_lshl_b64 s[2:3], s[96:97], 11
	s_add_u32 s24, s27, s2
	s_addc_u32 s25, s28, s3
	v_ashrrev_i32_e32 v17, 31, v16
	v_lshl_add_u64 v[48:49], v[12:13], 0, v[16:17]
	global_load_dwordx2 v[50:51], v0, s[20:21] sc1
	global_load_dwordx2 v[52:53], v0, s[22:23] sc1
	global_load_dwordx2 v[14:15], v0, s[24:25] sc1
	s_waitcnt vmcnt(0)
	v_add_f32_e32 v30, 0, v32
	v_add_f32_e32 v31, 0, v33
	v_add_f32_e32 v30, v30, v50
	v_add_f32_e32 v31, v31, v51
	v_add_f32_e32 v30, v30, v52
	v_add_f32_e32 v31, v31, v53
	v_add_f32_e32 v0, v30, v14
	v_mul_f32_e32 v0, 0x3a800000, v0
	v_add_f32_e32 v14, v31, v15
	v_mul_f32_e32 v15, v0, v0
	v_fma_f32 v14, v14, s67, -v15
	v_max_f32_e32 v14, 0, v14
	v_add_f32_e32 v14, 0x3727c5ac, v14
	v_cmp_gt_f32_e32 vcc, s63, v14
	v_mul_f32_e32 v15, 0x4b800000, v14
	v_pk_add_f32 v[32:33], v[178:179], v[0:1] op_sel_hi:[1,0] neg_lo:[0,1] neg_hi:[0,1]
	v_cndmask_b32_e32 v14, v14, v15, vcc
	v_rsq_f32_e32 v14, v14
	s_nop 0
	v_mul_f32_e32 v15, 0x45800000, v14
	v_cndmask_b32_e32 v30, v14, v15, vcc
	v_lshlrev_b64 v[14:15], 2, v[16:17]
	v_lshl_add_u64 v[12:13], s[12:13], 0, v[14:15]
	v_lshl_add_u64 v[14:15], s[14:15], 0, v[14:15]
	global_load_dwordx4 v[50:53], v[12:13], off
	global_load_dwordx4 v[74:77], v[14:15], off
	v_pk_mul_f32 v[32:33], v[32:33], v[30:31] op_sel_hi:[1,0]
	s_waitcnt vmcnt(0)
	v_pk_fma_f32 v[50:51], v[50:51], v[32:33], v[74:75]
	v_pk_add_f32 v[32:33], v[180:181], v[0:1] op_sel_hi:[1,0] neg_lo:[0,1] neg_hi:[0,1]
	s_nop 0
	v_pk_mul_f32 v[32:33], v[32:33], v[30:31] op_sel_hi:[1,0]
	s_nop 0
	v_pk_fma_f32 v[52:53], v[52:53], v[32:33], v[76:77]
	v_lshl_add_u64 v[32:33], v[48:49], 2, s[8:9]
	global_store_dwordx4 v[32:33], v[50:53], off
	global_load_dwordx4 v[74:77], v[12:13], off offset:16
	global_load_dwordx4 v[78:81], v[14:15], off offset:16
	v_cvt_pk_bf16_f32 v50, v50, v51
	v_cvt_pk_bf16_f32 v51, v52, v53
	v_pk_add_f32 v[52:53], v[158:159], v[0:1] op_sel_hi:[1,0] neg_lo:[0,1] neg_hi:[0,1]
	v_lshl_add_u64 v[48:49], v[48:49], 1, s[6:7]
	v_pk_mul_f32 v[52:53], v[52:53], v[30:31] op_sel_hi:[1,0]
	s_waitcnt vmcnt(0)
	v_pk_fma_f32 v[74:75], v[74:75], v[52:53], v[78:79]
	v_pk_add_f32 v[52:53], v[160:161], v[0:1] op_sel_hi:[1,0] neg_lo:[0,1] neg_hi:[0,1]
	v_pk_add_f32 v[78:79], v[154:155], v[0:1] op_sel_hi:[1,0] neg_lo:[0,1] neg_hi:[0,1]
	v_pk_mul_f32 v[52:53], v[52:53], v[30:31] op_sel_hi:[1,0]
	v_pk_mul_f32 v[78:79], v[78:79], v[30:31] op_sel_hi:[1,0]
	v_pk_fma_f32 v[76:77], v[76:77], v[52:53], v[80:81]
	v_cvt_pk_bf16_f32 v52, v74, v75
	v_cvt_pk_bf16_f32 v53, v76, v77
	global_store_dwordx4 v[32:33], v[74:77], off offset:16
	global_store_dwordx4 v[48:49], v[50:53], off
	global_load_dwordx4 v[50:53], v[12:13], off offset:32
	s_nop 0
	global_load_dwordx4 v[74:77], v[14:15], off offset:32
	s_waitcnt vmcnt(0)
	v_pk_fma_f32 v[50:51], v[50:51], v[78:79], v[74:75]
	v_pk_add_f32 v[74:75], v[156:157], v[0:1] op_sel_hi:[1,0] neg_lo:[0,1] neg_hi:[0,1]
	s_nop 0
	v_pk_mul_f32 v[74:75], v[74:75], v[30:31] op_sel_hi:[1,0]
	s_nop 0
	v_pk_fma_f32 v[52:53], v[52:53], v[74:75], v[76:77]
	global_store_dwordx4 v[32:33], v[50:53], off offset:32
	global_load_dwordx4 v[74:77], v[12:13], off offset:48
	global_load_dwordx4 v[78:81], v[14:15], off offset:48
	v_cvt_pk_bf16_f32 v50, v50, v51
	v_cvt_pk_bf16_f32 v51, v52, v53
	v_pk_add_f32 v[52:53], v[152:153], v[0:1] op_sel_hi:[1,0] neg_lo:[0,1] neg_hi:[0,1]
	s_nop 0
	v_pk_mul_f32 v[52:53], v[52:53], v[30:31] op_sel_hi:[1,0]
	s_waitcnt vmcnt(0)
	v_pk_fma_f32 v[74:75], v[74:75], v[52:53], v[78:79]
	v_pk_add_f32 v[52:53], v[150:151], v[0:1] op_sel_hi:[1,0] neg_lo:[0,1] neg_hi:[0,1]
	s_nop 0
	v_pk_mul_f32 v[52:53], v[52:53], v[30:31] op_sel_hi:[1,0]
	s_nop 0
	v_pk_fma_f32 v[76:77], v[76:77], v[52:53], v[80:81]
	v_cvt_pk_bf16_f32 v52, v74, v75
	v_cvt_pk_bf16_f32 v53, v76, v77
	global_store_dwordx4 v[32:33], v[74:77], off offset:48
	global_store_dwordx4 v[48:49], v[50:53], off offset:16
	global_load_dwordx4 v[50:53], v[12:13], off offset:128
	s_nop 0
	global_load_dwordx4 v[74:77], v[14:15], off offset:128
	v_pk_add_f32 v[78:79], v[144:145], v[0:1] op_sel_hi:[1,0] neg_lo:[0,1] neg_hi:[0,1]
	v_pk_add_f32 v[80:81], v[148:149], v[0:1] op_sel_hi:[1,0] neg_lo:[0,1] neg_hi:[0,1]
	v_pk_mul_f32 v[78:79], v[78:79], v[30:31] op_sel_hi:[1,0]
	v_pk_mul_f32 v[80:81], v[80:81], v[30:31] op_sel_hi:[1,0]
	v_pk_add_f32 v[82:83], v[138:139], v[0:1] op_sel_hi:[1,0] neg_lo:[0,1] neg_hi:[0,1]
	v_pk_add_f32 v[84:85], v[146:147], v[0:1] op_sel_hi:[1,0] neg_lo:[0,1] neg_hi:[0,1]
	v_pk_mul_f32 v[82:83], v[82:83], v[30:31] op_sel_hi:[1,0]
	v_pk_mul_f32 v[84:85], v[84:85], v[30:31] op_sel_hi:[1,0]
	s_waitcnt vmcnt(0)
	v_pk_fma_f32 v[50:51], v[78:79], v[50:51], v[74:75]
	v_pk_fma_f32 v[52:53], v[80:81], v[52:53], v[76:77]
	global_store_dwordx4 v[32:33], v[50:53], off offset:128
	global_load_dwordx4 v[74:77], v[12:13], off offset:144
	global_load_dwordx4 v[78:81], v[14:15], off offset:144
	v_cvt_pk_bf16_f32 v50, v50, v51
	v_cvt_pk_bf16_f32 v51, v52, v53
	s_waitcnt vmcnt(0)
; DI unsigned pk2(float lo, float hi) { f32x2 v = {lo, hi}; bf16x2v b = __builtin_convertvector(v, bf16x2v); return __builtin_bit_cast(unsigned, b); }
;   DI void full(const int mt_, const int nt_, f32x16 (&acc)[2][2][2], const int tw, const int fw, const int r, const int hh, char* lds, const int tid) const {
;     ...
; #pragma unroll
;       for (int half = 0; half < 2; ++half)
; #pragma unroll
;         for (int nt = 0; nt < 2; ++nt) {
; #pragma unroll
;           for (int gp = 0; gp < 2; ++gp) {
;             const int co = half * 64 + nt * 32 + 8 * gp;
;             u32x4 ob;
; #pragma unroll
;             for (int h2 = 0; h2 < 2; ++h2) {
;               f32x4 gv = *(const f32x4*)(g + c0 + co + 4 * h2), bv = *(const f32x4*)(b + c0 + co + 4 * h2), o;
; #pragma unroll
;               for (int jj = 0; jj < 4; ++jj) o[jj] = (acc[half][nt][mt][8 * gp + 4 * h2 + jj] - mean) * rstd * gv[jj] + bv[jj];
;               *(f32x4*)(xout + rowo + co + 4 * h2) = o;
;               ob[2 * h2] = pk2(o[0], o[1]); ob[2 * h2 + 1] = pk2(o[2], o[3]);
;             }
;             *(u32x4*)(xb + rowo + co) = ob;
;           }
;           __builtin_amdgcn_sched_barrier(0);
;         }
	v_pk_fma_f32 v[74:75], v[82:83], v[74:75], v[78:79]
	v_pk_fma_f32 v[76:77], v[84:85], v[76:77], v[80:81]
	v_cvt_pk_bf16_f32 v52, v74, v75
	v_cvt_pk_bf16_f32 v53, v76, v77
	global_store_dwordx4 v[32:33], v[74:77], off offset:144
	global_store_dwordx4 v[48:49], v[50:53], off offset:64
	global_load_dwordx4 v[50:53], v[12:13], off offset:160
	s_nop 0
	global_load_dwordx4 v[74:77], v[14:15], off offset:160
	v_pk_add_f32 v[78:79], v[130:131], v[0:1] op_sel_hi:[1,0] neg_lo:[0,1] neg_hi:[0,1]
	v_pk_add_f32 v[80:81], v[140:141], v[0:1] op_sel_hi:[1,0] neg_lo:[0,1] neg_hi:[0,1]
	v_pk_mul_f32 v[78:79], v[78:79], v[30:31] op_sel_hi:[1,0]
	v_pk_mul_f32 v[80:81], v[80:81], v[30:31] op_sel_hi:[1,0]
	v_pk_add_f32 v[82:83], v[124:125], v[0:1] op_sel_hi:[1,0] neg_lo:[0,1] neg_hi:[0,1]
	v_pk_add_f32 v[84:85], v[134:135], v[0:1] op_sel_hi:[1,0] neg_lo:[0,1] neg_hi:[0,1]
	v_pk_mul_f32 v[82:83], v[82:83], v[30:31] op_sel_hi:[1,0]
	v_pk_mul_f32 v[84:85], v[84:85], v[30:31] op_sel_hi:[1,0]
	s_waitcnt vmcnt(0)
	v_pk_fma_f32 v[50:51], v[78:79], v[50:51], v[74:75]
	v_pk_fma_f32 v[52:53], v[80:81], v[52:53], v[76:77]
	global_store_dwordx4 v[32:33], v[50:53], off offset:160
	global_load_dwordx4 v[74:77], v[12:13], off offset:176
	global_load_dwordx4 v[78:81], v[14:15], off offset:176
	v_cvt_pk_bf16_f32 v50, v50, v51
	v_cvt_pk_bf16_f32 v51, v52, v53
	s_waitcnt vmcnt(0)
	v_pk_fma_f32 v[74:75], v[82:83], v[74:75], v[78:79]
	v_pk_fma_f32 v[76:77], v[84:85], v[76:77], v[80:81]
	v_cvt_pk_bf16_f32 v52, v74, v75
	v_cvt_pk_bf16_f32 v53, v76, v77
	global_store_dwordx4 v[32:33], v[74:77], off offset:176
	global_store_dwordx4 v[48:49], v[50:53], off offset:80
	global_load_dwordx4 v[50:53], v[12:13], off offset:256
	s_nop 0
	global_load_dwordx4 v[74:77], v[14:15], off offset:256
	v_pk_add_f32 v[78:79], v[132:133], v[0:1] op_sel_hi:[1,0] neg_lo:[0,1] neg_hi:[0,1]
	v_pk_add_f32 v[80:81], v[142:143], v[0:1] op_sel_hi:[1,0] neg_lo:[0,1] neg_hi:[0,1]
	v_pk_mul_f32 v[78:79], v[78:79], v[30:31] op_sel_hi:[1,0]
	v_pk_mul_f32 v[80:81], v[80:81], v[30:31] op_sel_hi:[1,0]
	v_pk_add_f32 v[82:83], v[126:127], v[0:1] op_sel_hi:[1,0] neg_lo:[0,1] neg_hi:[0,1]
	v_pk_add_f32 v[84:85], v[136:137], v[0:1] op_sel_hi:[1,0] neg_lo:[0,1] neg_hi:[0,1]
	v_pk_mul_f32 v[82:83], v[82:83], v[30:31] op_sel_hi:[1,0]
	v_pk_mul_f32 v[84:85], v[84:85], v[30:31] op_sel_hi:[1,0]
	s_waitcnt vmcnt(0)
	v_pk_fma_f32 v[50:51], v[78:79], v[50:51], v[74:75]
	v_pk_fma_f32 v[52:53], v[80:81], v[52:53], v[76:77]
	global_store_dwordx4 v[32:33], v[50:53], off offset:256
	global_load_dwordx4 v[74:77], v[12:13], off offset:272
	global_load_dwordx4 v[78:81], v[14:15], off offset:272
	v_cvt_pk_bf16_f32 v50, v50, v51
	v_cvt_pk_bf16_f32 v51, v52, v53
	s_waitcnt vmcnt(0)
	v_pk_fma_f32 v[74:75], v[82:83], v[74:75], v[78:79]
	v_pk_fma_f32 v[76:77], v[84:85], v[76:77], v[80:81]
	v_cvt_pk_bf16_f32 v52, v74, v75
	v_cvt_pk_bf16_f32 v53, v76, v77
	global_store_dwordx4 v[32:33], v[74:77], off offset:272
	global_store_dwordx4 v[48:49], v[50:53], off offset:128
	global_load_dwordx4 v[50:53], v[12:13], off offset:288
	s_nop 0
	global_load_dwordx4 v[74:77], v[14:15], off offset:288
	v_pk_add_f32 v[78:79], v[112:113], v[0:1] op_sel_hi:[1,0] neg_lo:[0,1] neg_hi:[0,1]
	v_pk_add_f32 v[80:81], v[128:129], v[0:1] op_sel_hi:[1,0] neg_lo:[0,1] neg_hi:[0,1]
	v_pk_mul_f32 v[78:79], v[78:79], v[30:31] op_sel_hi:[1,0]
	v_pk_mul_f32 v[80:81], v[80:81], v[30:31] op_sel_hi:[1,0]
	v_pk_add_f32 v[82:83], v[106:107], v[0:1] op_sel_hi:[1,0] neg_lo:[0,1] neg_hi:[0,1]
	v_pk_add_f32 v[84:85], v[118:119], v[0:1] op_sel_hi:[1,0] neg_lo:[0,1] neg_hi:[0,1]
	v_pk_mul_f32 v[82:83], v[82:83], v[30:31] op_sel_hi:[1,0]
	v_pk_mul_f32 v[84:85], v[84:85], v[30:31] op_sel_hi:[1,0]
	s_waitcnt vmcnt(0)
	v_pk_fma_f32 v[50:51], v[78:79], v[50:51], v[74:75]
	v_pk_fma_f32 v[52:53], v[80:81], v[52:53], v[76:77]
	global_store_dwordx4 v[32:33], v[50:53], off offset:288
	global_load_dwordx4 v[74:77], v[12:13], off offset:304
	global_load_dwordx4 v[78:81], v[14:15], off offset:304
	v_cvt_pk_bf16_f32 v50, v50, v51
	v_cvt_pk_bf16_f32 v51, v52, v53
	s_waitcnt vmcnt(0)
	v_pk_fma_f32 v[74:75], v[82:83], v[74:75], v[78:79]
	v_pk_fma_f32 v[76:77], v[84:85], v[76:77], v[80:81]
	v_cvt_pk_bf16_f32 v52, v74, v75
	v_cvt_pk_bf16_f32 v53, v76, v77
	global_store_dwordx4 v[32:33], v[74:77], off offset:304
	global_store_dwordx4 v[48:49], v[50:53], off offset:144
	global_load_dwordx4 v[50:53], v[12:13], off offset:384
	s_nop 0
	global_load_dwordx4 v[74:77], v[14:15], off offset:384
	v_pk_add_f32 v[78:79], v[104:105], v[0:1] op_sel_hi:[1,0] neg_lo:[0,1] neg_hi:[0,1]
	v_pk_add_f32 v[80:81], v[122:123], v[0:1] op_sel_hi:[1,0] neg_lo:[0,1] neg_hi:[0,1]
	v_pk_mul_f32 v[78:79], v[78:79], v[30:31] op_sel_hi:[1,0]
	v_pk_mul_f32 v[80:81], v[80:81], v[30:31] op_sel_hi:[1,0]
	v_pk_add_f32 v[82:83], v[102:103], v[0:1] op_sel_hi:[1,0] neg_lo:[0,1] neg_hi:[0,1]
	v_pk_add_f32 v[84:85], v[120:121], v[0:1] op_sel_hi:[1,0] neg_lo:[0,1] neg_hi:[0,1]
	v_pk_mul_f32 v[82:83], v[82:83], v[30:31] op_sel_hi:[1,0]
	v_pk_mul_f32 v[84:85], v[84:85], v[30:31] op_sel_hi:[1,0]
	s_waitcnt vmcnt(0)
	v_pk_fma_f32 v[50:51], v[78:79], v[50:51], v[74:75]
	v_pk_fma_f32 v[52:53], v[80:81], v[52:53], v[76:77]
	global_store_dwordx4 v[32:33], v[50:53], off offset:384
	global_load_dwordx4 v[74:77], v[12:13], off offset:400
	global_load_dwordx4 v[78:81], v[14:15], off offset:400
	v_cvt_pk_bf16_f32 v50, v50, v51
	v_cvt_pk_bf16_f32 v51, v52, v53
	s_waitcnt vmcnt(0)
; #define GAS __attribute__((address_space(1)))
; DI unsigned pk2(float lo, float hi) { f32x2 v = {lo, hi}; bf16x2v b = __builtin_convertvector(v, bf16x2v); return __builtin_bit_cast(unsigned, b); }
;   DI void full(const int mt_, const int nt_, f32x16 (&acc)[2][2][2], const int tw, const int fw, const int r, const int hh, char* lds, const int tid) const {
;     ...
;     for (int mt = 0; mt < 2; ++mt) {
;       const int tl = tw * 64 + mt * 32 + r;
;       float S = 0.f, Q = 0.f;
; #pragma unroll
;       for (int k = 0; k < 4; ++k) {
;         const unsigned long long pk = __hip_atomic_load((GAS unsigned long long*)(xchg + ((size_t)(mt_ * 4 + k) * 256 + tl) * 2), __ATOMIC_RELAXED, __HIP_MEMORY_SCOPE_AGENT);
;         S += __uint_as_float((unsigned)pk);
;         Q += __uint_as_float((unsigned)(pk >> 32));
;       }
;       const float mean = S * (1.f / 1024.f);
;       const float rstd = rsqrtf(fmaxf(Q * (1.f / 1024.f) - mean * mean, 0.f) + 1e-5f);
;       const int c0 = nt_ * 256 + fw * 128 + 16 * hh;
;       const size_t rowo = (size_t)(mt_ * 256 + tl) * 1024 + c0;
; #pragma unroll
;       for (int half = 0; half < 2; ++half)
; #pragma unroll
;         for (int nt = 0; nt < 2; ++nt) {
; #pragma unroll
;           for (int gp = 0; gp < 2; ++gp) {
;             const int co = half * 64 + nt * 32 + 8 * gp;
;             u32x4 ob;
; #pragma unroll
;             for (int h2 = 0; h2 < 2; ++h2) {
;               f32x4 gv = *(const f32x4*)(g + c0 + co + 4 * h2), bv = *(const f32x4*)(b + c0 + co + 4 * h2), o;
; #pragma unroll
;               for (int jj = 0; jj < 4; ++jj) o[jj] = (acc[half][nt][mt][8 * gp + 4 * h2 + jj] - mean) * rstd * gv[jj] + bv[jj];
;               *(f32x4*)(xout + rowo + co + 4 * h2) = o;
;               ob[2 * h2] = pk2(o[0], o[1]); ob[2 * h2 + 1] = pk2(o[2], o[3]);
;             }
;             *(u32x4*)(xb + rowo + co) = ob;
;           }
;           __builtin_amdgcn_sched_barrier(0);
;         }
	v_pk_fma_f32 v[74:75], v[82:83], v[74:75], v[78:79]
	v_pk_fma_f32 v[76:77], v[84:85], v[76:77], v[80:81]
	v_cvt_pk_bf16_f32 v52, v74, v75
	v_cvt_pk_bf16_f32 v53, v76, v77
	global_store_dwordx4 v[32:33], v[74:77], off offset:400
	global_store_dwordx4 v[48:49], v[50:53], off offset:192
	global_load_dwordx4 v[50:53], v[12:13], off offset:416
	s_nop 0
	global_load_dwordx4 v[74:77], v[14:15], off offset:416
	v_pk_add_f32 v[78:79], v[94:95], v[0:1] op_sel_hi:[1,0] neg_lo:[0,1] neg_hi:[0,1]
	v_pk_add_f32 v[80:81], v[108:109], v[0:1] op_sel_hi:[1,0] neg_lo:[0,1] neg_hi:[0,1]
	v_pk_mul_f32 v[78:79], v[78:79], v[30:31] op_sel_hi:[1,0]
	v_pk_mul_f32 v[80:81], v[80:81], v[30:31] op_sel_hi:[1,0]
	v_pk_add_f32 v[82:83], v[96:97], v[0:1] op_sel_hi:[1,0] neg_lo:[0,1] neg_hi:[0,1]
	v_pk_add_f32 v[84:85], v[110:111], v[0:1] op_sel_hi:[1,0] neg_lo:[0,1] neg_hi:[0,1]
	v_pk_mul_f32 v[82:83], v[82:83], v[30:31] op_sel_hi:[1,0]
	v_pk_mul_f32 v[84:85], v[84:85], v[30:31] op_sel_hi:[1,0]
	s_waitcnt vmcnt(0)
	v_pk_fma_f32 v[50:51], v[78:79], v[50:51], v[74:75]
	v_pk_fma_f32 v[52:53], v[80:81], v[52:53], v[76:77]
	global_store_dwordx4 v[32:33], v[50:53], off offset:416
	global_load_dwordx4 v[74:77], v[12:13], off offset:432
	global_load_dwordx4 v[78:81], v[14:15], off offset:432
	v_cvt_pk_bf16_f32 v30, v50, v51
	v_cvt_pk_bf16_f32 v31, v52, v53
	s_waitcnt vmcnt(0)
	v_pk_fma_f32 v[50:51], v[82:83], v[74:75], v[78:79]
	v_pk_fma_f32 v[52:53], v[84:85], v[76:77], v[80:81]
	global_store_dwordx4 v[32:33], v[50:53], off offset:432
	v_cvt_pk_bf16_f32 v32, v50, v51
	v_cvt_pk_bf16_f32 v33, v52, v53
	global_store_dwordx4 v[48:49], v[30:33], off offset:208
	v_or_b32_e32 v0, 32, v223
	s_nop 0
	v_lshlrev_b32_e32 v32, 3, v0
	global_load_dwordx2 v[78:79], v32, s[18:19] sc1
	v_or_b32_e32 v0, s4, v0
	global_load_dwordx2 v[80:81], v32, s[20:21] sc1
	global_load_dwordx2 v[30:31], v32, s[24:25] sc1
	global_load_dwordx2 v[32:33], v32, s[22:23] sc1
	global_load_dwordx4 v[50:53], v[12:13], off
	global_load_dwordx4 v[74:77], v[14:15], off
	s_waitcnt vmcnt(2)
	v_add_f32_e32 v48, 0, v79
	v_add_f32_e32 v48, v48, v81
	v_add_f32_e32 v48, v48, v33
	v_add_f32_e32 v33, 0, v78
	v_add_f32_e32 v33, v33, v80
	v_add_f32_e32 v33, v33, v32
	v_add_f32_e32 v30, v33, v30
	v_mul_f32_e32 v30, 0x3a800000, v30
	v_add_f32_e32 v31, v48, v31
	v_mul_f32_e32 v32, v30, v30
	v_fma_f32 v31, v31, s67, -v32
	v_max_f32_e32 v31, 0, v31
	v_add_f32_e32 v31, 0x3727c5ac, v31
	v_cmp_gt_f32_e32 vcc, s63, v31
	v_mul_f32_e32 v32, 0x4b800000, v31
	v_lshlrev_b64 v[48:49], 10, v[0:1]
	v_cndmask_b32_e32 v31, v31, v32, vcc
	v_rsq_f32_e32 v31, v31
	v_lshl_add_u64 v[48:49], v[48:49], 0, v[16:17]
	v_mul_f32_e32 v32, 0x45800000, v31
	v_cndmask_b32_e32 v32, v31, v32, vcc
	v_pk_add_f32 v[16:17], v[90:91], v[30:31] op_sel_hi:[1,0] neg_lo:[0,1] neg_hi:[0,1]
	v_pk_add_f32 v[70:71], v[70:71], v[30:31] op_sel_hi:[1,0] neg_lo:[0,1] neg_hi:[0,1]
	v_pk_mul_f32 v[16:17], v[16:17], v[32:33] op_sel_hi:[1,0]
	v_pk_mul_f32 v[70:71], v[70:71], v[32:33] op_sel_hi:[1,0]
	s_waitcnt vmcnt(0)
	v_pk_fma_f32 v[50:51], v[50:51], v[16:17], v[74:75]
	v_pk_add_f32 v[16:17], v[92:93], v[30:31] op_sel_hi:[1,0] neg_lo:[0,1] neg_hi:[0,1]
	s_nop 0
	v_pk_mul_f32 v[16:17], v[16:17], v[32:33] op_sel_hi:[1,0]
	s_nop 0
	v_pk_fma_f32 v[52:53], v[52:53], v[16:17], v[76:77]
	v_lshl_add_u64 v[16:17], v[48:49], 2, s[8:9]
	global_store_dwordx4 v[16:17], v[50:53], off
	global_load_dwordx4 v[74:77], v[12:13], off offset:16
	global_load_dwordx4 v[78:81], v[14:15], off offset:16
	v_cvt_pk_bf16_f32 v50, v50, v51
	v_cvt_pk_bf16_f32 v51, v52, v53
	v_pk_add_f32 v[52:53], v[86:87], v[30:31] op_sel_hi:[1,0] neg_lo:[0,1] neg_hi:[0,1]
	v_lshl_add_u64 v[48:49], v[48:49], 1, s[6:7]
	v_pk_mul_f32 v[52:53], v[52:53], v[32:33] op_sel_hi:[1,0]
	s_waitcnt vmcnt(0)
	v_pk_fma_f32 v[74:75], v[74:75], v[52:53], v[78:79]
	v_pk_add_f32 v[52:53], v[88:89], v[30:31] op_sel_hi:[1,0] neg_lo:[0,1] neg_hi:[0,1]
	s_nop 0
	v_pk_mul_f32 v[52:53], v[52:53], v[32:33] op_sel_hi:[1,0]
	s_nop 0
	v_pk_fma_f32 v[76:77], v[76:77], v[52:53], v[80:81]
	v_cvt_pk_bf16_f32 v52, v74, v75
	v_cvt_pk_bf16_f32 v53, v76, v77
	global_store_dwordx4 v[16:17], v[74:77], off offset:16
	global_store_dwordx4 v[48:49], v[50:53], off
	global_load_dwordx4 v[50:53], v[12:13], off offset:32
	s_nop 0
	global_load_dwordx4 v[74:77], v[14:15], off offset:32
	s_waitcnt vmcnt(0)
	v_pk_fma_f32 v[50:51], v[50:51], v[70:71], v[74:75]
	v_pk_add_f32 v[70:71], v[72:73], v[30:31] op_sel_hi:[1,0] neg_lo:[0,1] neg_hi:[0,1]
	s_nop 0
	v_pk_mul_f32 v[70:71], v[70:71], v[32:33] op_sel_hi:[1,0]
	s_nop 0
	v_pk_fma_f32 v[52:53], v[52:53], v[70:71], v[76:77]
	global_store_dwordx4 v[16:17], v[50:53], off offset:32
	global_load_dwordx4 v[70:73], v[12:13], off offset:48
	global_load_dwordx4 v[74:77], v[14:15], off offset:48
	v_cvt_pk_bf16_f32 v50, v50, v51
	v_cvt_pk_bf16_f32 v51, v52, v53
	v_pk_add_f32 v[52:53], v[68:69], v[30:31] op_sel_hi:[1,0] neg_lo:[0,1] neg_hi:[0,1]
	s_nop 0
	v_pk_mul_f32 v[52:53], v[52:53], v[32:33] op_sel_hi:[1,0]
	s_waitcnt vmcnt(0)
; DI unsigned pk2(float lo, float hi) { f32x2 v = {lo, hi}; bf16x2v b = __builtin_convertvector(v, bf16x2v); return __builtin_bit_cast(unsigned, b); }
;   DI void full(const int mt_, const int nt_, f32x16 (&acc)[2][2][2], const int tw, const int fw, const int r, const int hh, char* lds, const int tid) const {
;     ...
; #pragma unroll
;       for (int half = 0; half < 2; ++half)
; #pragma unroll
;         for (int nt = 0; nt < 2; ++nt) {
; #pragma unroll
;           for (int gp = 0; gp < 2; ++gp) {
;             const int co = half * 64 + nt * 32 + 8 * gp;
;             u32x4 ob;
; #pragma unroll
;             for (int h2 = 0; h2 < 2; ++h2) {
;               f32x4 gv = *(const f32x4*)(g + c0 + co + 4 * h2), bv = *(const f32x4*)(b + c0 + co + 4 * h2), o;
; #pragma unroll
;               for (int jj = 0; jj < 4; ++jj) o[jj] = (acc[half][nt][mt][8 * gp + 4 * h2 + jj] - mean) * rstd * gv[jj] + bv[jj];
;               *(f32x4*)(xout + rowo + co + 4 * h2) = o;
;               ob[2 * h2] = pk2(o[0], o[1]); ob[2 * h2 + 1] = pk2(o[2], o[3]);
;             }
;             *(u32x4*)(xb + rowo + co) = ob;
;           }
;           __builtin_amdgcn_sched_barrier(0);
;         }
	v_pk_fma_f32 v[68:69], v[70:71], v[52:53], v[74:75]
	v_pk_add_f32 v[52:53], v[66:67], v[30:31] op_sel_hi:[1,0] neg_lo:[0,1] neg_hi:[0,1]
	s_nop 0
	v_pk_mul_f32 v[52:53], v[52:53], v[32:33] op_sel_hi:[1,0]
	s_nop 0
	v_pk_fma_f32 v[70:71], v[72:73], v[52:53], v[76:77]
	v_cvt_pk_bf16_f32 v52, v68, v69
	v_cvt_pk_bf16_f32 v53, v70, v71
	global_store_dwordx4 v[16:17], v[68:71], off offset:48
	global_store_dwordx4 v[48:49], v[50:53], off offset:16
	global_load_dwordx4 v[50:53], v[12:13], off offset:128
	s_nop 0
	global_load_dwordx4 v[66:69], v[14:15], off offset:128
	v_pk_add_f32 v[60:61], v[60:61], v[30:31] op_sel_hi:[1,0] neg_lo:[0,1] neg_hi:[0,1]
	v_pk_add_f32 v[64:65], v[64:65], v[30:31] op_sel_hi:[1,0] neg_lo:[0,1] neg_hi:[0,1]
	v_pk_mul_f32 v[60:61], v[60:61], v[32:33] op_sel_hi:[1,0]
	v_pk_mul_f32 v[64:65], v[64:65], v[32:33] op_sel_hi:[1,0]
	v_pk_add_f32 v[56:57], v[56:57], v[30:31] op_sel_hi:[1,0] neg_lo:[0,1] neg_hi:[0,1]
	v_pk_add_f32 v[54:55], v[54:55], v[30:31] op_sel_hi:[1,0] neg_lo:[0,1] neg_hi:[0,1]
	v_pk_mul_f32 v[56:57], v[56:57], v[32:33] op_sel_hi:[1,0]
	v_pk_mul_f32 v[54:55], v[54:55], v[32:33] op_sel_hi:[1,0]
	v_pk_add_f32 v[44:45], v[44:45], v[30:31] op_sel_hi:[1,0] neg_lo:[0,1] neg_hi:[0,1]
	v_pk_add_f32 v[46:47], v[46:47], v[30:31] op_sel_hi:[1,0] neg_lo:[0,1] neg_hi:[0,1]
	s_waitcnt vmcnt(0)
	v_pk_fma_f32 v[50:51], v[60:61], v[50:51], v[66:67]
	v_pk_fma_f32 v[52:53], v[64:65], v[52:53], v[68:69]
	global_store_dwordx4 v[16:17], v[50:53], off offset:128
	global_load_dwordx4 v[64:67], v[12:13], off offset:144
	global_load_dwordx4 v[68:71], v[14:15], off offset:144
	v_pk_add_f32 v[60:61], v[62:63], v[30:31] op_sel_hi:[1,0] neg_lo:[0,1] neg_hi:[0,1]
	v_cvt_pk_bf16_f32 v50, v50, v51
	v_pk_mul_f32 v[62:63], v[60:61], v[32:33] op_sel_hi:[1,0]
	v_cvt_pk_bf16_f32 v51, v52, v53
	v_pk_mul_f32 v[46:47], v[46:47], v[32:33] op_sel_hi:[1,0]
	s_waitcnt vmcnt(0)
	v_pk_fma_f32 v[60:61], v[56:57], v[64:65], v[68:69]
	v_pk_fma_f32 v[62:63], v[62:63], v[66:67], v[70:71]
	v_cvt_pk_bf16_f32 v52, v60, v61
	v_cvt_pk_bf16_f32 v53, v62, v63
	global_store_dwordx4 v[16:17], v[60:63], off offset:144
	global_store_dwordx4 v[48:49], v[50:53], off offset:64
	global_load_dwordx4 v[50:53], v[12:13], off offset:160
	s_nop 0
	global_load_dwordx4 v[60:63], v[14:15], off offset:160
	v_pk_add_f32 v[56:57], v[58:59], v[30:31] op_sel_hi:[1,0] neg_lo:[0,1] neg_hi:[0,1]
	s_waitcnt vmcnt(0)
	v_pk_fma_f32 v[50:51], v[54:55], v[50:51], v[60:61]
	v_pk_mul_f32 v[56:57], v[56:57], v[32:33] op_sel_hi:[1,0]
	s_nop 0
	v_pk_fma_f32 v[52:53], v[56:57], v[52:53], v[62:63]
	global_store_dwordx4 v[16:17], v[50:53], off offset:160
	global_load_dwordx4 v[54:57], v[12:13], off offset:176
	global_load_dwordx4 v[58:61], v[14:15], off offset:176
	v_pk_mul_f32 v[62:63], v[44:45], v[32:33] op_sel_hi:[1,0]
	v_cvt_pk_bf16_f32 v44, v50, v51
	v_cvt_pk_bf16_f32 v45, v52, v53
	s_waitcnt vmcnt(0)
	v_pk_fma_f32 v[50:51], v[62:63], v[54:55], v[58:59]
	v_pk_fma_f32 v[52:53], v[46:47], v[56:57], v[60:61]
	v_cvt_pk_bf16_f32 v46, v50, v51
	v_cvt_pk_bf16_f32 v47, v52, v53
	global_store_dwordx4 v[16:17], v[50:53], off offset:176
	global_store_dwordx4 v[48:49], v[44:47], off offset:80
	global_load_dwordx4 v[44:47], v[12:13], off offset:256
	s_nop 0
	global_load_dwordx4 v[50:53], v[14:15], off offset:256
	v_pk_add_f32 v[38:39], v[38:39], v[30:31] op_sel_hi:[1,0] neg_lo:[0,1] neg_hi:[0,1]
	v_pk_add_f32 v[42:43], v[42:43], v[30:31] op_sel_hi:[1,0] neg_lo:[0,1] neg_hi:[0,1]
	v_pk_mul_f32 v[38:39], v[38:39], v[32:33] op_sel_hi:[1,0]
	v_pk_mul_f32 v[54:55], v[42:43], v[32:33] op_sel_hi:[1,0]
	v_pk_add_f32 v[34:35], v[34:35], v[30:31] op_sel_hi:[1,0] neg_lo:[0,1] neg_hi:[0,1]
	v_pk_add_f32 v[26:27], v[26:27], v[30:31] op_sel_hi:[1,0] neg_lo:[0,1] neg_hi:[0,1]
	v_pk_mul_f32 v[34:35], v[34:35], v[32:33] op_sel_hi:[1,0]
	v_pk_mul_f32 v[26:27], v[26:27], v[32:33] op_sel_hi:[1,0]
	v_pk_add_f32 v[24:25], v[24:25], v[30:31] op_sel_hi:[1,0] neg_lo:[0,1] neg_hi:[0,1]
	s_waitcnt vmcnt(0)
	v_pk_fma_f32 v[42:43], v[38:39], v[44:45], v[50:51]
	v_pk_fma_f32 v[44:45], v[54:55], v[46:47], v[52:53]
	global_store_dwordx4 v[16:17], v[42:45], off offset:256
	global_load_dwordx4 v[50:53], v[12:13], off offset:272
	global_load_dwordx4 v[54:57], v[14:15], off offset:272
	v_pk_add_f32 v[38:39], v[40:41], v[30:31] op_sel_hi:[1,0] neg_lo:[0,1] neg_hi:[0,1]
	s_waitcnt vmcnt(0)
; DI unsigned pk2(float lo, float hi) { f32x2 v = {lo, hi}; bf16x2v b = __builtin_convertvector(v, bf16x2v); return __builtin_bit_cast(unsigned, b); }
;   DI void full(const int mt_, const int nt_, f32x16 (&acc)[2][2][2], const int tw, const int fw, const int r, const int hh, char* lds, const int tid) const {
;     ...
; #pragma unroll
;       for (int half = 0; half < 2; ++half)
; #pragma unroll
;         for (int nt = 0; nt < 2; ++nt) {
; #pragma unroll
;           for (int gp = 0; gp < 2; ++gp) {
;             const int co = half * 64 + nt * 32 + 8 * gp;
;             u32x4 ob;
; #pragma unroll
;             for (int h2 = 0; h2 < 2; ++h2) {
;               f32x4 gv = *(const f32x4*)(g + c0 + co + 4 * h2), bv = *(const f32x4*)(b + c0 + co + 4 * h2), o;
; #pragma unroll
;               for (int jj = 0; jj < 4; ++jj) o[jj] = (acc[half][nt][mt][8 * gp + 4 * h2 + jj] - mean) * rstd * gv[jj] + bv[jj];
;               *(f32x4*)(xout + rowo + co + 4 * h2) = o;
;               ob[2 * h2] = pk2(o[0], o[1]); ob[2 * h2 + 1] = pk2(o[2], o[3]);
;             }
;             *(u32x4*)(xb + rowo + co) = ob;
;           }
;           __builtin_amdgcn_sched_barrier(0);
;         }
;     }
;     __syncthreads();
	v_pk_fma_f32 v[40:41], v[34:35], v[50:51], v[54:55]
	v_pk_mul_f32 v[46:47], v[38:39], v[32:33] op_sel_hi:[1,0]
	v_cvt_pk_bf16_f32 v38, v42, v43
	v_pk_fma_f32 v[42:43], v[46:47], v[52:53], v[56:57]
	v_cvt_pk_bf16_f32 v39, v44, v45
	global_store_dwordx4 v[16:17], v[40:43], off offset:272
	v_pk_add_f32 v[34:35], v[36:37], v[30:31] op_sel_hi:[1,0] neg_lo:[0,1] neg_hi:[0,1]
	s_nop 0
	v_cvt_pk_bf16_f32 v40, v40, v41
	v_cvt_pk_bf16_f32 v41, v42, v43
	global_store_dwordx4 v[48:49], v[38:41], off offset:128
	global_load_dwordx4 v[38:41], v[12:13], off offset:288
	s_nop 0
	global_load_dwordx4 v[42:45], v[14:15], off offset:288
	v_pk_mul_f32 v[36:37], v[34:35], v[32:33] op_sel_hi:[1,0]
	s_waitcnt vmcnt(0)
	v_pk_fma_f32 v[34:35], v[26:27], v[38:39], v[42:43]
	v_pk_fma_f32 v[36:37], v[36:37], v[40:41], v[44:45]
	global_store_dwordx4 v[16:17], v[34:37], off offset:288
	global_load_dwordx4 v[38:41], v[12:13], off offset:304
	global_load_dwordx4 v[42:45], v[14:15], off offset:304
	v_pk_add_f32 v[26:27], v[28:29], v[30:31] op_sel_hi:[1,0] neg_lo:[0,1] neg_hi:[0,1]
	v_pk_mul_f32 v[28:29], v[24:25], v[32:33] op_sel_hi:[1,0]
	v_pk_mul_f32 v[46:47], v[26:27], v[32:33] op_sel_hi:[1,0]
	v_cvt_pk_bf16_f32 v24, v34, v35
	v_cvt_pk_bf16_f32 v25, v36, v37
	s_waitcnt vmcnt(0)
	v_pk_fma_f32 v[26:27], v[28:29], v[38:39], v[42:43]
	v_pk_fma_f32 v[28:29], v[46:47], v[40:41], v[44:45]
	global_store_dwordx4 v[16:17], v[26:29], off offset:304
	s_nop 1
	v_cvt_pk_bf16_f32 v26, v26, v27
	v_cvt_pk_bf16_f32 v27, v28, v29
	global_store_dwordx4 v[48:49], v[24:27], off offset:144
	global_load_dwordx4 v[24:27], v[12:13], off offset:384
	s_nop 0
	global_load_dwordx4 v[34:37], v[14:15], off offset:384
	v_pk_add_f32 v[18:19], v[18:19], v[30:31] op_sel_hi:[1,0] neg_lo:[0,1] neg_hi:[0,1]
	v_pk_add_f32 v[22:23], v[22:23], v[30:31] op_sel_hi:[1,0] neg_lo:[0,1] neg_hi:[0,1]
	v_pk_mul_f32 v[18:19], v[18:19], v[32:33] op_sel_hi:[1,0]
	v_pk_mul_f32 v[28:29], v[22:23], v[32:33] op_sel_hi:[1,0]
	v_pk_add_f32 v[6:7], v[6:7], v[30:31] op_sel_hi:[1,0] neg_lo:[0,1] neg_hi:[0,1]
	v_pk_add_f32 v[2:3], v[2:3], v[30:31] op_sel_hi:[1,0] neg_lo:[0,1] neg_hi:[0,1]
	v_pk_mul_f32 v[6:7], v[6:7], v[32:33] op_sel_hi:[1,0]
	v_pk_mul_f32 v[2:3], v[2:3], v[32:33] op_sel_hi:[1,0]
	s_waitcnt vmcnt(0)
	v_pk_fma_f32 v[22:23], v[18:19], v[24:25], v[34:35]
	v_pk_fma_f32 v[24:25], v[28:29], v[26:27], v[36:37]
	global_store_dwordx4 v[16:17], v[22:25], off offset:384
	global_load_dwordx4 v[26:29], v[12:13], off offset:400
	global_load_dwordx4 v[34:37], v[14:15], off offset:400
	v_pk_add_f32 v[18:19], v[20:21], v[30:31] op_sel_hi:[1,0] neg_lo:[0,1] neg_hi:[0,1]
	s_waitcnt vmcnt(0)
	v_pk_fma_f32 v[20:21], v[6:7], v[26:27], v[34:35]
	v_pk_mul_f32 v[38:39], v[18:19], v[32:33] op_sel_hi:[1,0]
	v_cvt_pk_bf16_f32 v18, v22, v23
	v_pk_fma_f32 v[22:23], v[38:39], v[28:29], v[36:37]
	v_cvt_pk_bf16_f32 v19, v24, v25
	global_store_dwordx4 v[16:17], v[20:23], off offset:400
	v_pk_add_f32 v[6:7], v[8:9], v[30:31] op_sel_hi:[1,0] neg_lo:[0,1] neg_hi:[0,1]
	s_nop 0
	v_cvt_pk_bf16_f32 v20, v20, v21
	v_cvt_pk_bf16_f32 v21, v22, v23
	global_store_dwordx4 v[48:49], v[18:21], off offset:192
	global_load_dwordx4 v[18:21], v[12:13], off offset:416
	s_nop 0
	global_load_dwordx4 v[22:25], v[14:15], off offset:416
	v_pk_mul_f32 v[8:9], v[6:7], v[32:33] op_sel_hi:[1,0]
	s_waitcnt vmcnt(0)
	v_pk_fma_f32 v[6:7], v[2:3], v[18:19], v[22:23]
	v_pk_fma_f32 v[8:9], v[8:9], v[20:21], v[24:25]
	global_store_dwordx4 v[16:17], v[6:9], off offset:416
	global_load_dwordx4 v[18:21], v[12:13], off offset:432
	s_nop 0
	global_load_dwordx4 v[12:15], v[14:15], off offset:432
	v_pk_add_f32 v[2:3], v[4:5], v[30:31] op_sel_hi:[1,0] neg_lo:[0,1] neg_hi:[0,1]
	v_pk_add_f32 v[4:5], v[10:11], v[30:31] op_sel_hi:[1,0] neg_lo:[0,1] neg_hi:[0,1]
	v_pk_mul_f32 v[10:11], v[2:3], v[32:33] op_sel_hi:[1,0]
	v_pk_mul_f32 v[22:23], v[4:5], v[32:33] op_sel_hi:[1,0]
	v_cvt_pk_bf16_f32 v2, v6, v7
	v_cvt_pk_bf16_f32 v3, v8, v9
	s_waitcnt vmcnt(0)
	v_pk_fma_f32 v[4:5], v[10:11], v[18:19], v[12:13]
	v_pk_fma_f32 v[6:7], v[22:23], v[20:21], v[14:15]
	global_store_dwordx4 v[16:17], v[4:7], off offset:432
	s_nop 1
	v_cvt_pk_bf16_f32 v4, v4, v5
	v_cvt_pk_bf16_f32 v5, v6, v7
	global_store_dwordx4 v[48:49], v[2:5], off offset:208
	s_barrier
	s_add_i32 s2, s34, 8
	s_cmp_gt_u32 s34, 7
	s_mov_b32 s34, s2
	s_cbranch_scc1 .LBB0_711

; #define GAS __attribute__((address_space(1)))
; DI unsigned pk2(float lo, float hi) { f32x2 v = {lo, hi}; bf16x2v b = __builtin_convertvector(v, bf16x2v); return __builtin_bit_cast(unsigned, b); }
;   DI void full(const int mt_, const int nt_, f32x16 (&acc)[2][2][2], const int tw, const int fw, const int r, const int hh, char* lds, const int tid) const {
;     ...
; #pragma unroll
;     for (int mt = 0; mt < 2; ++mt) {
;       const int tl = tw * 64 + mt * 32 + r;
;       float S = 0.f, Q = 0.f;
; #pragma unroll
;       for (int k = 0; k < 4; ++k) {
;         const unsigned long long pk = __hip_atomic_load((GAS unsigned long long*)(xchg + ((size_t)(mt_ * 4 + k) * 256 + tl) * 2), __ATOMIC_RELAXED, __HIP_MEMORY_SCOPE_AGENT);
;         S += __uint_as_float((unsigned)pk);
;         Q += __uint_as_float((unsigned)(pk >> 32));
;       }
;       const float mean = S * (1.f / 1024.f);
;       const float rstd = rsqrtf(fmaxf(Q * (1.f / 1024.f) - mean * mean, 0.f) + 1e-5f);
;       const int c0 = nt_ * 256 + fw * 128 + 16 * hh;
;       const size_t rowo = (size_t)(mt_ * 256 + tl) * 1024 + c0;
; #pragma unroll
;       for (int half = 0; half < 2; ++half)
; #pragma unroll
;         for (int nt = 0; nt < 2; ++nt) {
; #pragma unroll
;           for (int gp = 0; gp < 2; ++gp) {
;             const int co = half * 64 + nt * 32 + 8 * gp;
;             u32x4 ob;
; #pragma unroll
;             for (int h2 = 0; h2 < 2; ++h2) {
;               f32x4 gv = *(const f32x4*)(g + c0 + co + 4 * h2), bv = *(const f32x4*)(b + c0 + co + 4 * h2), o;
; #pragma unroll
;               for (int jj = 0; jj < 4; ++jj) o[jj] = (acc[half][nt][mt][8 * gp + 4 * h2 + jj] - mean) * rstd * gv[jj] + bv[jj];
;               *(f32x4*)(xout + rowo + co + 4 * h2) = o;
;               ob[2 * h2] = pk2(o[0], o[1]); ob[2 * h2 + 1] = pk2(o[2], o[3]);
;             }
;             *(u32x4*)(xb + rowo + co) = ob;
;           }
;           __builtin_amdgcn_sched_barrier(0);
;         }
.LBB0_767:
	s_or_b64 exec, exec, s[4:5]
	s_lshl_b32 s96, s36, 2
	s_lshl_b64 s[4:5], s[96:97], 11
	v_lshlrev_b64 v[12:13], 10, v[0:1]
	v_lshlrev_b32_e32 v0, 4, v226
	v_add_u32_e32 v14, s48, v184
	s_add_u32 s4, s26, s4
	v_or_b32_e32 v16, v0, v14
	s_addc_u32 s5, s27, s5
	v_lshlrev_b32_e32 v0, 3, v225
	s_barrier
	global_load_dwordx2 v[32:33], v0, s[4:5] sc1
	s_or_b32 s18, s96, 1
	s_mov_b32 s19, s97
	s_lshl_b64 s[18:19], s[18:19], 11
	s_add_u32 s18, s26, s18
	s_addc_u32 s19, s27, s19
	s_or_b32 s20, s96, 2
	s_mov_b32 s21, s97
	s_lshl_b64 s[20:21], s[20:21], 11
	s_add_u32 s20, s26, s20
	s_addc_u32 s21, s27, s21
	s_or_b32 s96, s96, 3
	s_lshl_b64 s[22:23], s[96:97], 11
	s_add_u32 s22, s26, s22
	s_addc_u32 s23, s27, s23
	v_ashrrev_i32_e32 v17, 31, v16
	v_lshl_add_u64 v[34:35], v[12:13], 0, v[16:17]
	global_load_dwordx2 v[36:37], v0, s[18:19] sc1
	global_load_dwordx2 v[58:59], v0, s[20:21] sc1
	global_load_dwordx2 v[14:15], v0, s[22:23] sc1
	s_waitcnt vmcnt(0)
	v_add_f32_e32 v30, 0, v32
	v_add_f32_e32 v31, 0, v33
	v_add_f32_e32 v30, v30, v36
	v_add_f32_e32 v31, v31, v37
	v_add_f32_e32 v30, v30, v58
	v_add_f32_e32 v31, v31, v59
	v_add_f32_e32 v0, v30, v14
	v_mul_f32_e32 v0, 0x3a800000, v0
	v_add_f32_e32 v14, v31, v15
	v_mul_f32_e32 v15, v0, v0
	v_fma_f32 v14, v14, s67, -v15
	v_max_f32_e32 v14, 0, v14
	v_add_f32_e32 v14, 0x3727c5ac, v14
	v_cmp_gt_f32_e32 vcc, s63, v14
	v_mul_f32_e32 v15, 0x4b800000, v14
	v_pk_add_f32 v[32:33], v[180:181], v[0:1] op_sel_hi:[1,0] neg_lo:[0,1] neg_hi:[0,1]
	v_cndmask_b32_e32 v14, v14, v15, vcc
	v_rsq_f32_e32 v14, v14
	v_pk_add_f32 v[36:37], v[160:161], v[0:1] op_sel_hi:[1,0] neg_lo:[0,1] neg_hi:[0,1]
	v_mul_f32_e32 v15, 0x45800000, v14
	v_cndmask_b32_e32 v30, v14, v15, vcc
	v_lshlrev_b64 v[14:15], 2, v[16:17]
	v_lshl_add_u64 v[12:13], s[8:9], 0, v[14:15]
	v_lshl_add_u64 v[14:15], s[10:11], 0, v[14:15]
	global_load_dwordx4 v[58:61], v[12:13], off
	global_load_dwordx4 v[62:65], v[14:15], off
	v_pk_mul_f32 v[32:33], v[32:33], v[30:31] op_sel_hi:[1,0]
	v_pk_mul_f32 v[36:37], v[36:37], v[30:31] op_sel_hi:[1,0]
	s_waitcnt vmcnt(0)
	v_pk_fma_f32 v[58:59], v[58:59], v[32:33], v[62:63]
	v_pk_add_f32 v[32:33], v[182:183], v[0:1] op_sel_hi:[1,0] neg_lo:[0,1] neg_hi:[0,1]
	s_nop 0
	v_pk_mul_f32 v[32:33], v[32:33], v[30:31] op_sel_hi:[1,0]
	s_nop 0
	v_pk_fma_f32 v[60:61], v[60:61], v[32:33], v[64:65]
	v_lshl_add_u64 v[32:33], v[34:35], 2, s[12:13]
	global_store_dwordx4 v[32:33], v[58:61], off
	v_lshl_add_u64 v[34:35], v[34:35], 1, s[6:7]
	s_nop 0
	v_cvt_pk_bf16_f32 v58, v58, v59
	v_cvt_pk_bf16_f32 v59, v60, v61
	global_load_dwordx4 v[60:63], v[12:13], off offset:16
	global_load_dwordx4 v[78:81], v[14:15], off offset:16
	s_waitcnt vmcnt(0)
	v_pk_fma_f32 v[60:61], v[60:61], v[36:37], v[78:79]
	v_pk_add_f32 v[36:37], v[178:179], v[0:1] op_sel_hi:[1,0] neg_lo:[0,1] neg_hi:[0,1]
	s_nop 0
	v_pk_mul_f32 v[36:37], v[36:37], v[30:31] op_sel_hi:[1,0]
	s_nop 0
	v_pk_fma_f32 v[62:63], v[62:63], v[36:37], v[80:81]
	global_store_dwordx4 v[32:33], v[60:63], off offset:16
	v_pk_add_f32 v[36:37], v[156:157], v[0:1] op_sel_hi:[1,0] neg_lo:[0,1] neg_hi:[0,1]
	s_nop 0
	v_cvt_pk_bf16_f32 v60, v60, v61
	v_cvt_pk_bf16_f32 v61, v62, v63
	global_store_dwordx4 v[34:35], v[58:61], off
	global_load_dwordx4 v[58:61], v[12:13], off offset:32
	s_nop 0
	global_load_dwordx4 v[62:65], v[14:15], off offset:32
	v_pk_mul_f32 v[36:37], v[36:37], v[30:31] op_sel_hi:[1,0]
	s_waitcnt vmcnt(0)
	v_pk_fma_f32 v[58:59], v[58:59], v[36:37], v[62:63]
	v_pk_add_f32 v[36:37], v[158:159], v[0:1] op_sel_hi:[1,0] neg_lo:[0,1] neg_hi:[0,1]
	s_nop 0
	v_pk_mul_f32 v[36:37], v[36:37], v[30:31] op_sel_hi:[1,0]
	s_nop 0
	v_pk_fma_f32 v[60:61], v[60:61], v[36:37], v[64:65]
	global_store_dwordx4 v[32:33], v[58:61], off offset:32
	v_pk_add_f32 v[36:37], v[154:155], v[0:1] op_sel_hi:[1,0] neg_lo:[0,1] neg_hi:[0,1]
	s_nop 0
	v_cvt_pk_bf16_f32 v58, v58, v59
	v_cvt_pk_bf16_f32 v59, v60, v61
	global_load_dwordx4 v[60:63], v[12:13], off offset:48
	global_load_dwordx4 v[78:81], v[14:15], off offset:48
	v_pk_mul_f32 v[36:37], v[36:37], v[30:31] op_sel_hi:[1,0]
	s_waitcnt vmcnt(0)
	v_pk_fma_f32 v[60:61], v[60:61], v[36:37], v[78:79]
	v_pk_add_f32 v[36:37], v[152:153], v[0:1] op_sel_hi:[1,0] neg_lo:[0,1] neg_hi:[0,1]
	s_nop 0
	v_pk_mul_f32 v[36:37], v[36:37], v[30:31] op_sel_hi:[1,0]
	s_nop 0
	v_pk_fma_f32 v[62:63], v[62:63], v[36:37], v[80:81]
	global_store_dwordx4 v[32:33], v[60:63], off offset:48
	s_nop 1
	v_cvt_pk_bf16_f32 v60, v60, v61
	v_cvt_pk_bf16_f32 v61, v62, v63
	global_store_dwordx4 v[34:35], v[58:61], off offset:16
	global_load_dwordx4 v[58:61], v[12:13], off offset:128
	s_nop 0
	global_load_dwordx4 v[62:65], v[14:15], off offset:128
	v_pk_add_f32 v[36:37], v[146:147], v[0:1] op_sel_hi:[1,0] neg_lo:[0,1] neg_hi:[0,1]
	v_pk_add_f32 v[78:79], v[150:151], v[0:1] op_sel_hi:[1,0] neg_lo:[0,1] neg_hi:[0,1]
	v_pk_mul_f32 v[36:37], v[36:37], v[30:31] op_sel_hi:[1,0]
	v_pk_mul_f32 v[78:79], v[78:79], v[30:31] op_sel_hi:[1,0]
	v_pk_add_f32 v[82:83], v[148:149], v[0:1] op_sel_hi:[1,0] neg_lo:[0,1] neg_hi:[0,1]
	s_waitcnt vmcnt(0)
	v_pk_fma_f32 v[58:59], v[36:37], v[58:59], v[62:63]
	v_pk_fma_f32 v[60:61], v[78:79], v[60:61], v[64:65]
	global_store_dwordx4 v[32:33], v[58:61], off offset:128
	global_load_dwordx4 v[62:65], v[12:13], off offset:144
	global_load_dwordx4 v[78:81], v[14:15], off offset:144
	v_pk_add_f32 v[36:37], v[140:141], v[0:1] op_sel_hi:[1,0] neg_lo:[0,1] neg_hi:[0,1]
	v_pk_mul_f32 v[82:83], v[82:83], v[30:31] op_sel_hi:[1,0]
	v_pk_mul_f32 v[36:37], v[36:37], v[30:31] op_sel_hi:[1,0]
	v_cvt_pk_bf16_f32 v58, v58, v59
	v_cvt_pk_bf16_f32 v59, v60, v61
	s_waitcnt vmcnt(0)
; DI unsigned pk2(float lo, float hi) { f32x2 v = {lo, hi}; bf16x2v b = __builtin_convertvector(v, bf16x2v); return __builtin_bit_cast(unsigned, b); }
;   DI void full(const int mt_, const int nt_, f32x16 (&acc)[2][2][2], const int tw, const int fw, const int r, const int hh, char* lds, const int tid) const {
;     ...
; #pragma unroll
;       for (int half = 0; half < 2; ++half)
; #pragma unroll
;         for (int nt = 0; nt < 2; ++nt) {
; #pragma unroll
;           for (int gp = 0; gp < 2; ++gp) {
;             const int co = half * 64 + nt * 32 + 8 * gp;
;             u32x4 ob;
; #pragma unroll
;             for (int h2 = 0; h2 < 2; ++h2) {
;               f32x4 gv = *(const f32x4*)(g + c0 + co + 4 * h2), bv = *(const f32x4*)(b + c0 + co + 4 * h2), o;
; #pragma unroll
;               for (int jj = 0; jj < 4; ++jj) o[jj] = (acc[half][nt][mt][8 * gp + 4 * h2 + jj] - mean) * rstd * gv[jj] + bv[jj];
;               *(f32x4*)(xout + rowo + co + 4 * h2) = o;
;               ob[2 * h2] = pk2(o[0], o[1]); ob[2 * h2 + 1] = pk2(o[2], o[3]);
;             }
;             *(u32x4*)(xb + rowo + co) = ob;
;           }
;           __builtin_amdgcn_sched_barrier(0);
;         }
	v_pk_fma_f32 v[60:61], v[36:37], v[62:63], v[78:79]
	v_pk_fma_f32 v[62:63], v[82:83], v[64:65], v[80:81]
	global_store_dwordx4 v[32:33], v[60:63], off offset:144
	v_pk_add_f32 v[36:37], v[132:133], v[0:1] op_sel_hi:[1,0] neg_lo:[0,1] neg_hi:[0,1]
	v_pk_add_f32 v[78:79], v[142:143], v[0:1] op_sel_hi:[1,0] neg_lo:[0,1] neg_hi:[0,1]
	v_cvt_pk_bf16_f32 v60, v60, v61
	v_cvt_pk_bf16_f32 v61, v62, v63
	global_store_dwordx4 v[34:35], v[58:61], off offset:64
	global_load_dwordx4 v[58:61], v[12:13], off offset:160
	s_nop 0
	global_load_dwordx4 v[62:65], v[14:15], off offset:160
	v_pk_mul_f32 v[36:37], v[36:37], v[30:31] op_sel_hi:[1,0]
	v_pk_mul_f32 v[78:79], v[78:79], v[30:31] op_sel_hi:[1,0]
	v_pk_add_f32 v[82:83], v[136:137], v[0:1] op_sel_hi:[1,0] neg_lo:[0,1] neg_hi:[0,1]
	s_waitcnt vmcnt(0)
	v_pk_fma_f32 v[58:59], v[36:37], v[58:59], v[62:63]
	v_pk_fma_f32 v[60:61], v[78:79], v[60:61], v[64:65]
	global_store_dwordx4 v[32:33], v[58:61], off offset:160
	global_load_dwordx4 v[62:65], v[12:13], off offset:176
	global_load_dwordx4 v[78:81], v[14:15], off offset:176
	v_pk_add_f32 v[36:37], v[126:127], v[0:1] op_sel_hi:[1,0] neg_lo:[0,1] neg_hi:[0,1]
	v_pk_mul_f32 v[82:83], v[82:83], v[30:31] op_sel_hi:[1,0]
	v_pk_mul_f32 v[36:37], v[36:37], v[30:31] op_sel_hi:[1,0]
	v_cvt_pk_bf16_f32 v58, v58, v59
	v_cvt_pk_bf16_f32 v59, v60, v61
	s_waitcnt vmcnt(0)
	v_pk_fma_f32 v[60:61], v[36:37], v[62:63], v[78:79]
	v_pk_fma_f32 v[62:63], v[82:83], v[64:65], v[80:81]
	global_store_dwordx4 v[32:33], v[60:63], off offset:176
	s_nop 1
	v_cvt_pk_bf16_f32 v60, v60, v61
	v_cvt_pk_bf16_f32 v61, v62, v63
	global_store_dwordx4 v[34:35], v[58:61], off offset:80
	global_load_dwordx4 v[58:61], v[12:13], off offset:256
	s_nop 0
	global_load_dwordx4 v[62:65], v[14:15], off offset:256
	v_pk_add_f32 v[36:37], v[134:135], v[0:1] op_sel_hi:[1,0] neg_lo:[0,1] neg_hi:[0,1]
	v_pk_add_f32 v[78:79], v[144:145], v[0:1] op_sel_hi:[1,0] neg_lo:[0,1] neg_hi:[0,1]
	v_pk_mul_f32 v[36:37], v[36:37], v[30:31] op_sel_hi:[1,0]
	v_pk_mul_f32 v[78:79], v[78:79], v[30:31] op_sel_hi:[1,0]
	v_pk_add_f32 v[82:83], v[138:139], v[0:1] op_sel_hi:[1,0] neg_lo:[0,1] neg_hi:[0,1]
	s_waitcnt vmcnt(0)
	v_pk_fma_f32 v[58:59], v[36:37], v[58:59], v[62:63]
	v_pk_fma_f32 v[60:61], v[78:79], v[60:61], v[64:65]
	global_store_dwordx4 v[32:33], v[58:61], off offset:256
	global_load_dwordx4 v[62:65], v[12:13], off offset:272
	global_load_dwordx4 v[78:81], v[14:15], off offset:272
	v_pk_add_f32 v[36:37], v[128:129], v[0:1] op_sel_hi:[1,0] neg_lo:[0,1] neg_hi:[0,1]
	v_pk_mul_f32 v[82:83], v[82:83], v[30:31] op_sel_hi:[1,0]
	v_pk_mul_f32 v[36:37], v[36:37], v[30:31] op_sel_hi:[1,0]
	v_cvt_pk_bf16_f32 v58, v58, v59
	v_cvt_pk_bf16_f32 v59, v60, v61
	s_waitcnt vmcnt(0)
	v_pk_fma_f32 v[60:61], v[36:37], v[62:63], v[78:79]
	v_pk_fma_f32 v[62:63], v[82:83], v[64:65], v[80:81]
	global_store_dwordx4 v[32:33], v[60:63], off offset:272
	v_pk_add_f32 v[36:37], v[118:119], v[0:1] op_sel_hi:[1,0] neg_lo:[0,1] neg_hi:[0,1]
	v_pk_add_f32 v[78:79], v[130:131], v[0:1] op_sel_hi:[1,0] neg_lo:[0,1] neg_hi:[0,1]
	v_cvt_pk_bf16_f32 v60, v60, v61
	v_cvt_pk_bf16_f32 v61, v62, v63
	global_store_dwordx4 v[34:35], v[58:61], off offset:128
	global_load_dwordx4 v[58:61], v[12:13], off offset:288
	s_nop 0
	global_load_dwordx4 v[62:65], v[14:15], off offset:288
	v_pk_mul_f32 v[36:37], v[36:37], v[30:31] op_sel_hi:[1,0]
	v_pk_mul_f32 v[78:79], v[78:79], v[30:31] op_sel_hi:[1,0]
	v_pk_add_f32 v[82:83], v[120:121], v[0:1] op_sel_hi:[1,0] neg_lo:[0,1] neg_hi:[0,1]
	s_waitcnt vmcnt(0)
	v_pk_fma_f32 v[58:59], v[36:37], v[58:59], v[62:63]
	v_pk_fma_f32 v[60:61], v[78:79], v[60:61], v[64:65]
	global_store_dwordx4 v[32:33], v[58:61], off offset:288
	global_load_dwordx4 v[62:65], v[12:13], off offset:304
	global_load_dwordx4 v[78:81], v[14:15], off offset:304
	v_pk_add_f32 v[36:37], v[108:109], v[0:1] op_sel_hi:[1,0] neg_lo:[0,1] neg_hi:[0,1]
	v_pk_mul_f32 v[82:83], v[82:83], v[30:31] op_sel_hi:[1,0]
	v_pk_mul_f32 v[36:37], v[36:37], v[30:31] op_sel_hi:[1,0]
	v_cvt_pk_bf16_f32 v58, v58, v59
	v_cvt_pk_bf16_f32 v59, v60, v61
	s_waitcnt vmcnt(0)
	v_pk_fma_f32 v[60:61], v[36:37], v[62:63], v[78:79]
	v_pk_fma_f32 v[62:63], v[82:83], v[64:65], v[80:81]
	global_store_dwordx4 v[32:33], v[60:63], off offset:304
	s_nop 1
	v_cvt_pk_bf16_f32 v60, v60, v61
	v_cvt_pk_bf16_f32 v61, v62, v63
	global_store_dwordx4 v[34:35], v[58:61], off offset:144
	global_load_dwordx4 v[58:61], v[12:13], off offset:384
	s_nop 0
	global_load_dwordx4 v[62:65], v[14:15], off offset:384
	v_pk_add_f32 v[36:37], v[106:107], v[0:1] op_sel_hi:[1,0] neg_lo:[0,1] neg_hi:[0,1]
	v_pk_add_f32 v[78:79], v[124:125], v[0:1] op_sel_hi:[1,0] neg_lo:[0,1] neg_hi:[0,1]
	v_pk_mul_f32 v[36:37], v[36:37], v[30:31] op_sel_hi:[1,0]
	v_pk_mul_f32 v[78:79], v[78:79], v[30:31] op_sel_hi:[1,0]
	v_pk_add_f32 v[82:83], v[122:123], v[0:1] op_sel_hi:[1,0] neg_lo:[0,1] neg_hi:[0,1]
	s_waitcnt vmcnt(0)
	v_pk_fma_f32 v[58:59], v[36:37], v[58:59], v[62:63]
	v_pk_fma_f32 v[60:61], v[78:79], v[60:61], v[64:65]
	global_store_dwordx4 v[32:33], v[58:61], off offset:384
	global_load_dwordx4 v[62:65], v[12:13], off offset:400
	global_load_dwordx4 v[78:81], v[14:15], off offset:400
	v_pk_add_f32 v[36:37], v[104:105], v[0:1] op_sel_hi:[1,0] neg_lo:[0,1] neg_hi:[0,1]
	v_pk_mul_f32 v[82:83], v[82:83], v[30:31] op_sel_hi:[1,0]
	v_pk_mul_f32 v[36:37], v[36:37], v[30:31] op_sel_hi:[1,0]
	v_cvt_pk_bf16_f32 v58, v58, v59
	v_cvt_pk_bf16_f32 v59, v60, v61
	s_waitcnt vmcnt(0)
; #define GAS __attribute__((address_space(1)))
; DI unsigned pk2(float lo, float hi) { f32x2 v = {lo, hi}; bf16x2v b = __builtin_convertvector(v, bf16x2v); return __builtin_bit_cast(unsigned, b); }
;   DI void full(const int mt_, const int nt_, f32x16 (&acc)[2][2][2], const int tw, const int fw, const int r, const int hh, char* lds, const int tid) const {
;     ...
;     for (int mt = 0; mt < 2; ++mt) {
;       const int tl = tw * 64 + mt * 32 + r;
;       float S = 0.f, Q = 0.f;
; #pragma unroll
;       for (int k = 0; k < 4; ++k) {
;         const unsigned long long pk = __hip_atomic_load((GAS unsigned long long*)(xchg + ((size_t)(mt_ * 4 + k) * 256 + tl) * 2), __ATOMIC_RELAXED, __HIP_MEMORY_SCOPE_AGENT);
;         S += __uint_as_float((unsigned)pk);
;         Q += __uint_as_float((unsigned)(pk >> 32));
;       }
;       const float mean = S * (1.f / 1024.f);
;       const float rstd = rsqrtf(fmaxf(Q * (1.f / 1024.f) - mean * mean, 0.f) + 1e-5f);
;       const int c0 = nt_ * 256 + fw * 128 + 16 * hh;
;       const size_t rowo = (size_t)(mt_ * 256 + tl) * 1024 + c0;
; #pragma unroll
;       for (int half = 0; half < 2; ++half)
; #pragma unroll
;         for (int nt = 0; nt < 2; ++nt) {
; #pragma unroll
;           for (int gp = 0; gp < 2; ++gp) {
;             const int co = half * 64 + nt * 32 + 8 * gp;
;             u32x4 ob;
; #pragma unroll
;             for (int h2 = 0; h2 < 2; ++h2) {
;               f32x4 gv = *(const f32x4*)(g + c0 + co + 4 * h2), bv = *(const f32x4*)(b + c0 + co + 4 * h2), o;
; #pragma unroll
;               for (int jj = 0; jj < 4; ++jj) o[jj] = (acc[half][nt][mt][8 * gp + 4 * h2 + jj] - mean) * rstd * gv[jj] + bv[jj];
;               *(f32x4*)(xout + rowo + co + 4 * h2) = o;
;               ob[2 * h2] = pk2(o[0], o[1]); ob[2 * h2 + 1] = pk2(o[2], o[3]);
;             }
;             *(u32x4*)(xb + rowo + co) = ob;
;           }
;           __builtin_amdgcn_sched_barrier(0);
;         }
	v_pk_fma_f32 v[60:61], v[36:37], v[62:63], v[78:79]
	v_pk_fma_f32 v[62:63], v[82:83], v[64:65], v[80:81]
	global_store_dwordx4 v[32:33], v[60:63], off offset:400
	v_pk_add_f32 v[36:37], v[96:97], v[0:1] op_sel_hi:[1,0] neg_lo:[0,1] neg_hi:[0,1]
	v_pk_add_f32 v[78:79], v[110:111], v[0:1] op_sel_hi:[1,0] neg_lo:[0,1] neg_hi:[0,1]
	v_cvt_pk_bf16_f32 v60, v60, v61
	v_cvt_pk_bf16_f32 v61, v62, v63
	global_store_dwordx4 v[34:35], v[58:61], off offset:192
	global_load_dwordx4 v[58:61], v[12:13], off offset:416
	s_nop 0
	global_load_dwordx4 v[62:65], v[14:15], off offset:416
	v_pk_mul_f32 v[36:37], v[36:37], v[30:31] op_sel_hi:[1,0]
	v_pk_mul_f32 v[78:79], v[78:79], v[30:31] op_sel_hi:[1,0]
	v_pk_add_f32 v[82:83], v[112:113], v[0:1] op_sel_hi:[1,0] neg_lo:[0,1] neg_hi:[0,1]
	s_waitcnt vmcnt(0)
	v_pk_fma_f32 v[58:59], v[36:37], v[58:59], v[62:63]
	v_pk_fma_f32 v[60:61], v[78:79], v[60:61], v[64:65]
	global_store_dwordx4 v[32:33], v[58:61], off offset:416
	global_load_dwordx4 v[62:65], v[12:13], off offset:432
	global_load_dwordx4 v[78:81], v[14:15], off offset:432
	v_pk_add_f32 v[36:37], v[102:103], v[0:1] op_sel_hi:[1,0] neg_lo:[0,1] neg_hi:[0,1]
	v_pk_mul_f32 v[82:83], v[82:83], v[30:31] op_sel_hi:[1,0]
	v_pk_mul_f32 v[36:37], v[36:37], v[30:31] op_sel_hi:[1,0]
	v_cvt_pk_bf16_f32 v30, v58, v59
	v_cvt_pk_bf16_f32 v31, v60, v61
	s_waitcnt vmcnt(0)
	v_pk_fma_f32 v[58:59], v[36:37], v[62:63], v[78:79]
	v_pk_fma_f32 v[60:61], v[82:83], v[64:65], v[80:81]
	global_store_dwordx4 v[32:33], v[58:61], off offset:432
	v_cvt_pk_bf16_f32 v32, v58, v59
	v_cvt_pk_bf16_f32 v33, v60, v61
	global_store_dwordx4 v[34:35], v[30:33], off offset:208
	v_or_b32_e32 v0, 32, v225
	s_nop 0
	v_lshlrev_b32_e32 v32, 3, v0
	global_load_dwordx2 v[36:37], v32, s[4:5] sc1
	v_or_b32_e32 v0, s2, v0
	global_load_dwordx2 v[78:79], v32, s[18:19] sc1
	global_load_dwordx2 v[80:81], v32, s[20:21] sc1
	global_load_dwordx2 v[30:31], v32, s[22:23] sc1
	global_load_dwordx4 v[58:61], v[12:13], off
	global_load_dwordx4 v[62:65], v[14:15], off
	s_waitcnt vmcnt(2)
	v_add_f32_e32 v33, 0, v36
	v_add_f32_e32 v34, 0, v37
	v_add_f32_e32 v33, v33, v78
	v_add_f32_e32 v34, v34, v79
	v_add_f32_e32 v33, v33, v80
	v_add_f32_e32 v34, v34, v81
	v_add_f32_e32 v30, v33, v30
	v_mul_f32_e32 v30, 0x3a800000, v30
	v_add_f32_e32 v31, v34, v31
	v_mul_f32_e32 v32, v30, v30
	v_fma_f32 v31, v31, s67, -v32
	v_max_f32_e32 v31, 0, v31
	v_add_f32_e32 v31, 0x3727c5ac, v31
	v_cmp_gt_f32_e32 vcc, s63, v31
	v_mul_f32_e32 v32, 0x4b800000, v31
	v_lshlrev_b64 v[34:35], 10, v[0:1]
	v_cndmask_b32_e32 v31, v31, v32, vcc
	v_rsq_f32_e32 v31, v31
	v_lshl_add_u64 v[34:35], v[34:35], 0, v[16:17]
	v_mul_f32_e32 v32, 0x45800000, v31
	v_cndmask_b32_e32 v32, v31, v32, vcc
	v_pk_add_f32 v[16:17], v[92:93], v[30:31] op_sel_hi:[1,0] neg_lo:[0,1] neg_hi:[0,1]
	v_pk_add_f32 v[36:37], v[88:89], v[30:31] op_sel_hi:[1,0] neg_lo:[0,1] neg_hi:[0,1]
	v_pk_mul_f32 v[16:17], v[16:17], v[32:33] op_sel_hi:[1,0]
	v_pk_mul_f32 v[36:37], v[36:37], v[32:33] op_sel_hi:[1,0]
	s_waitcnt vmcnt(0)
	v_pk_fma_f32 v[58:59], v[58:59], v[16:17], v[62:63]
	v_pk_add_f32 v[16:17], v[94:95], v[30:31] op_sel_hi:[1,0] neg_lo:[0,1] neg_hi:[0,1]
	s_nop 0
	v_pk_mul_f32 v[16:17], v[16:17], v[32:33] op_sel_hi:[1,0]
	s_nop 0
	v_pk_fma_f32 v[60:61], v[60:61], v[16:17], v[64:65]
	v_lshl_add_u64 v[16:17], v[34:35], 2, s[12:13]
	global_store_dwordx4 v[16:17], v[58:61], off
	v_lshl_add_u64 v[34:35], v[34:35], 1, s[6:7]
	s_nop 0
	v_cvt_pk_bf16_f32 v58, v58, v59
	v_cvt_pk_bf16_f32 v59, v60, v61
	global_load_dwordx4 v[60:63], v[12:13], off offset:16
	global_load_dwordx4 v[78:81], v[14:15], off offset:16
	s_waitcnt vmcnt(0)
	v_pk_fma_f32 v[60:61], v[60:61], v[36:37], v[78:79]
	v_pk_add_f32 v[36:37], v[90:91], v[30:31] op_sel_hi:[1,0] neg_lo:[0,1] neg_hi:[0,1]
	s_nop 0
	v_pk_mul_f32 v[36:37], v[36:37], v[32:33] op_sel_hi:[1,0]
	s_nop 0
	v_pk_fma_f32 v[62:63], v[62:63], v[36:37], v[80:81]
	global_store_dwordx4 v[16:17], v[60:63], off offset:16
	v_pk_add_f32 v[36:37], v[86:87], v[30:31] op_sel_hi:[1,0] neg_lo:[0,1] neg_hi:[0,1]
	s_nop 0
	v_cvt_pk_bf16_f32 v60, v60, v61
	v_cvt_pk_bf16_f32 v61, v62, v63
	global_store_dwordx4 v[34:35], v[58:61], off
	global_load_dwordx4 v[58:61], v[12:13], off offset:32
	s_nop 0
	global_load_dwordx4 v[62:65], v[14:15], off offset:32
	v_pk_mul_f32 v[36:37], v[36:37], v[32:33] op_sel_hi:[1,0]
	s_waitcnt vmcnt(0)
	v_pk_fma_f32 v[58:59], v[58:59], v[36:37], v[62:63]
	v_pk_add_f32 v[36:37], v[76:77], v[30:31] op_sel_hi:[1,0] neg_lo:[0,1] neg_hi:[0,1]
	s_nop 0
	v_pk_mul_f32 v[36:37], v[36:37], v[32:33] op_sel_hi:[1,0]
	s_nop 0
	v_pk_fma_f32 v[60:61], v[60:61], v[36:37], v[64:65]
	global_store_dwordx4 v[16:17], v[58:61], off offset:32
	v_pk_add_f32 v[36:37], v[74:75], v[30:31] op_sel_hi:[1,0] neg_lo:[0,1] neg_hi:[0,1]
	s_nop 0
	v_cvt_pk_bf16_f32 v58, v58, v59
	v_cvt_pk_bf16_f32 v59, v60, v61
	global_load_dwordx4 v[60:63], v[12:13], off offset:48
	global_load_dwordx4 v[76:79], v[14:15], off offset:48
	v_pk_mul_f32 v[36:37], v[36:37], v[32:33] op_sel_hi:[1,0]
	s_waitcnt vmcnt(0)
	v_pk_fma_f32 v[60:61], v[60:61], v[36:37], v[76:77]
	v_pk_add_f32 v[36:37], v[72:73], v[30:31] op_sel_hi:[1,0] neg_lo:[0,1] neg_hi:[0,1]
	s_nop 0
	v_pk_mul_f32 v[36:37], v[36:37], v[32:33] op_sel_hi:[1,0]
	s_nop 0
	v_pk_fma_f32 v[62:63], v[62:63], v[36:37], v[78:79]
	global_store_dwordx4 v[16:17], v[60:63], off offset:48
	s_nop 1
	v_cvt_pk_bf16_f32 v60, v60, v61
	v_cvt_pk_bf16_f32 v61, v62, v63
	global_store_dwordx4 v[34:35], v[58:61], off offset:16
	global_load_dwordx4 v[58:61], v[12:13], off offset:128
	s_nop 0
	global_load_dwordx4 v[62:65], v[14:15], off offset:128
	v_pk_add_f32 v[36:37], v[66:67], v[30:31] op_sel_hi:[1,0] neg_lo:[0,1] neg_hi:[0,1]
	v_pk_add_f32 v[66:67], v[70:71], v[30:31] op_sel_hi:[1,0] neg_lo:[0,1] neg_hi:[0,1]
	v_pk_mul_f32 v[36:37], v[36:37], v[32:33] op_sel_hi:[1,0]
	v_pk_mul_f32 v[66:67], v[66:67], v[32:33] op_sel_hi:[1,0]
	s_waitcnt vmcnt(0)
; DI unsigned pk2(float lo, float hi) { f32x2 v = {lo, hi}; bf16x2v b = __builtin_convertvector(v, bf16x2v); return __builtin_bit_cast(unsigned, b); }
;   DI void full(const int mt_, const int nt_, f32x16 (&acc)[2][2][2], const int tw, const int fw, const int r, const int hh, char* lds, const int tid) const {
;     ...
; #pragma unroll
;       for (int half = 0; half < 2; ++half)
; #pragma unroll
;         for (int nt = 0; nt < 2; ++nt) {
; #pragma unroll
;           for (int gp = 0; gp < 2; ++gp) {
;             const int co = half * 64 + nt * 32 + 8 * gp;
;             u32x4 ob;
; #pragma unroll
;             for (int h2 = 0; h2 < 2; ++h2) {
;               f32x4 gv = *(const f32x4*)(g + c0 + co + 4 * h2), bv = *(const f32x4*)(b + c0 + co + 4 * h2), o;
; #pragma unroll
;               for (int jj = 0; jj < 4; ++jj) o[jj] = (acc[half][nt][mt][8 * gp + 4 * h2 + jj] - mean) * rstd * gv[jj] + bv[jj];
;               *(f32x4*)(xout + rowo + co + 4 * h2) = o;
;               ob[2 * h2] = pk2(o[0], o[1]); ob[2 * h2 + 1] = pk2(o[2], o[3]);
;             }
;             *(u32x4*)(xb + rowo + co) = ob;
;           }
;           __builtin_amdgcn_sched_barrier(0);
;         }
	v_pk_fma_f32 v[58:59], v[36:37], v[58:59], v[62:63]
	v_pk_fma_f32 v[60:61], v[66:67], v[60:61], v[64:65]
	global_store_dwordx4 v[16:17], v[58:61], off offset:128
	global_load_dwordx4 v[62:65], v[12:13], off offset:144
	global_load_dwordx4 v[70:73], v[14:15], off offset:144
	v_pk_add_f32 v[36:37], v[54:55], v[30:31] op_sel_hi:[1,0] neg_lo:[0,1] neg_hi:[0,1]
	v_pk_add_f32 v[54:55], v[68:69], v[30:31] op_sel_hi:[1,0] neg_lo:[0,1] neg_hi:[0,1]
	v_pk_mul_f32 v[36:37], v[36:37], v[32:33] op_sel_hi:[1,0]
	v_pk_mul_f32 v[54:55], v[54:55], v[32:33] op_sel_hi:[1,0]
	v_cvt_pk_bf16_f32 v58, v58, v59
	v_cvt_pk_bf16_f32 v59, v60, v61
	s_waitcnt vmcnt(0)
	v_pk_fma_f32 v[60:61], v[36:37], v[62:63], v[70:71]
	v_pk_fma_f32 v[62:63], v[54:55], v[64:65], v[72:73]
	global_store_dwordx4 v[16:17], v[60:63], off offset:144
	v_pk_add_f32 v[36:37], v[50:51], v[30:31] op_sel_hi:[1,0] neg_lo:[0,1] neg_hi:[0,1]
	v_pk_add_f32 v[50:51], v[56:57], v[30:31] op_sel_hi:[1,0] neg_lo:[0,1] neg_hi:[0,1]
	v_cvt_pk_bf16_f32 v60, v60, v61
	v_cvt_pk_bf16_f32 v61, v62, v63
	global_store_dwordx4 v[34:35], v[58:61], off offset:64
	global_load_dwordx4 v[58:61], v[12:13], off offset:160
	s_nop 0
	global_load_dwordx4 v[62:65], v[14:15], off offset:160
	v_pk_mul_f32 v[36:37], v[36:37], v[32:33] op_sel_hi:[1,0]
	v_pk_mul_f32 v[50:51], v[50:51], v[32:33] op_sel_hi:[1,0]
	s_waitcnt vmcnt(0)
	v_pk_fma_f32 v[54:55], v[36:37], v[58:59], v[62:63]
	v_pk_fma_f32 v[56:57], v[50:51], v[60:61], v[64:65]
	global_store_dwordx4 v[16:17], v[54:57], off offset:160
	global_load_dwordx4 v[58:61], v[12:13], off offset:176
	global_load_dwordx4 v[62:65], v[14:15], off offset:176
	v_pk_add_f32 v[36:37], v[48:49], v[30:31] op_sel_hi:[1,0] neg_lo:[0,1] neg_hi:[0,1]
	v_pk_add_f32 v[48:49], v[52:53], v[30:31] op_sel_hi:[1,0] neg_lo:[0,1] neg_hi:[0,1]
	v_pk_mul_f32 v[36:37], v[36:37], v[32:33] op_sel_hi:[1,0]
	v_pk_mul_f32 v[52:53], v[48:49], v[32:33] op_sel_hi:[1,0]
	v_cvt_pk_bf16_f32 v48, v54, v55
	v_cvt_pk_bf16_f32 v49, v56, v57
	s_waitcnt vmcnt(0)
	v_pk_fma_f32 v[50:51], v[36:37], v[58:59], v[62:63]
	v_pk_fma_f32 v[52:53], v[52:53], v[60:61], v[64:65]
	global_store_dwordx4 v[16:17], v[50:53], off offset:176
	s_nop 1
	v_cvt_pk_bf16_f32 v50, v50, v51
	v_cvt_pk_bf16_f32 v51, v52, v53
	global_store_dwordx4 v[34:35], v[48:51], off offset:80
	global_load_dwordx4 v[48:51], v[12:13], off offset:256
	s_nop 0
	global_load_dwordx4 v[52:55], v[14:15], off offset:256
	v_pk_add_f32 v[36:37], v[42:43], v[30:31] op_sel_hi:[1,0] neg_lo:[0,1] neg_hi:[0,1]
	v_pk_add_f32 v[42:43], v[46:47], v[30:31] op_sel_hi:[1,0] neg_lo:[0,1] neg_hi:[0,1]
	v_pk_mul_f32 v[36:37], v[36:37], v[32:33] op_sel_hi:[1,0]
	v_pk_mul_f32 v[42:43], v[42:43], v[32:33] op_sel_hi:[1,0]
	v_pk_add_f32 v[26:27], v[26:27], v[30:31] op_sel_hi:[1,0] neg_lo:[0,1] neg_hi:[0,1]
	v_pk_add_f32 v[40:41], v[40:41], v[30:31] op_sel_hi:[1,0] neg_lo:[0,1] neg_hi:[0,1]
	v_pk_mul_f32 v[26:27], v[26:27], v[32:33] op_sel_hi:[1,0]
	v_pk_mul_f32 v[40:41], v[40:41], v[32:33] op_sel_hi:[1,0]
	v_pk_add_f32 v[24:25], v[24:25], v[30:31] op_sel_hi:[1,0] neg_lo:[0,1] neg_hi:[0,1]
	s_waitcnt vmcnt(0)
	v_pk_fma_f32 v[46:47], v[36:37], v[48:49], v[52:53]
	v_pk_fma_f32 v[48:49], v[42:43], v[50:51], v[54:55]
	global_store_dwordx4 v[16:17], v[46:49], off offset:256
	global_load_dwordx4 v[50:53], v[12:13], off offset:272
	global_load_dwordx4 v[54:57], v[14:15], off offset:272
	v_pk_add_f32 v[36:37], v[38:39], v[30:31] op_sel_hi:[1,0] neg_lo:[0,1] neg_hi:[0,1]
	v_pk_add_f32 v[38:39], v[44:45], v[30:31] op_sel_hi:[1,0] neg_lo:[0,1] neg_hi:[0,1]
	v_pk_mul_f32 v[42:43], v[36:37], v[32:33] op_sel_hi:[1,0]
	v_pk_mul_f32 v[38:39], v[38:39], v[32:33] op_sel_hi:[1,0]
	v_cvt_pk_bf16_f32 v36, v46, v47
	v_cvt_pk_bf16_f32 v37, v48, v49
	s_waitcnt vmcnt(0)
; DI unsigned pk2(float lo, float hi) { f32x2 v = {lo, hi}; bf16x2v b = __builtin_convertvector(v, bf16x2v); return __builtin_bit_cast(unsigned, b); }
;   DI void full(const int mt_, const int nt_, f32x16 (&acc)[2][2][2], const int tw, const int fw, const int r, const int hh, char* lds, const int tid) const {
;     ...
; #pragma unroll
;       for (int half = 0; half < 2; ++half)
; #pragma unroll
;         for (int nt = 0; nt < 2; ++nt) {
; #pragma unroll
;           for (int gp = 0; gp < 2; ++gp) {
;             const int co = half * 64 + nt * 32 + 8 * gp;
;             u32x4 ob;
; #pragma unroll
;             for (int h2 = 0; h2 < 2; ++h2) {
;               f32x4 gv = *(const f32x4*)(g + c0 + co + 4 * h2), bv = *(const f32x4*)(b + c0 + co + 4 * h2), o;
; #pragma unroll
;               for (int jj = 0; jj < 4; ++jj) o[jj] = (acc[half][nt][mt][8 * gp + 4 * h2 + jj] - mean) * rstd * gv[jj] + bv[jj];
;               *(f32x4*)(xout + rowo + co + 4 * h2) = o;
;               ob[2 * h2] = pk2(o[0], o[1]); ob[2 * h2 + 1] = pk2(o[2], o[3]);
;             }
;             *(u32x4*)(xb + rowo + co) = ob;
;           }
;           __builtin_amdgcn_sched_barrier(0);
;         }
;     }
;     __syncthreads();
	v_pk_fma_f32 v[42:43], v[42:43], v[50:51], v[54:55]
	v_pk_fma_f32 v[44:45], v[38:39], v[52:53], v[56:57]
	v_cvt_pk_bf16_f32 v38, v42, v43
	v_cvt_pk_bf16_f32 v39, v44, v45
	global_store_dwordx4 v[16:17], v[42:45], off offset:272
	global_store_dwordx4 v[34:35], v[36:39], off offset:128
	global_load_dwordx4 v[36:39], v[12:13], off offset:288
	s_nop 0
	global_load_dwordx4 v[42:45], v[14:15], off offset:288
	s_waitcnt vmcnt(0)
	v_pk_fma_f32 v[36:37], v[26:27], v[36:37], v[42:43]
	v_pk_fma_f32 v[38:39], v[40:41], v[38:39], v[44:45]
	global_store_dwordx4 v[16:17], v[36:39], off offset:288
	global_load_dwordx4 v[40:43], v[12:13], off offset:304
	global_load_dwordx4 v[44:47], v[14:15], off offset:304
	v_pk_add_f32 v[26:27], v[28:29], v[30:31] op_sel_hi:[1,0] neg_lo:[0,1] neg_hi:[0,1]
	v_pk_mul_f32 v[28:29], v[24:25], v[32:33] op_sel_hi:[1,0]
	v_pk_mul_f32 v[48:49], v[26:27], v[32:33] op_sel_hi:[1,0]
	v_cvt_pk_bf16_f32 v24, v36, v37
	v_cvt_pk_bf16_f32 v25, v38, v39
	s_waitcnt vmcnt(0)
	v_pk_fma_f32 v[26:27], v[28:29], v[40:41], v[44:45]
	v_pk_fma_f32 v[28:29], v[48:49], v[42:43], v[46:47]
	global_store_dwordx4 v[16:17], v[26:29], off offset:304
	s_nop 1
	v_cvt_pk_bf16_f32 v26, v26, v27
	v_cvt_pk_bf16_f32 v27, v28, v29
	global_store_dwordx4 v[34:35], v[24:27], off offset:144
	global_load_dwordx4 v[24:27], v[12:13], off offset:384
	s_nop 0
	global_load_dwordx4 v[36:39], v[14:15], off offset:384
	v_pk_add_f32 v[18:19], v[18:19], v[30:31] op_sel_hi:[1,0] neg_lo:[0,1] neg_hi:[0,1]
	v_pk_add_f32 v[22:23], v[22:23], v[30:31] op_sel_hi:[1,0] neg_lo:[0,1] neg_hi:[0,1]
	v_pk_mul_f32 v[18:19], v[18:19], v[32:33] op_sel_hi:[1,0]
	v_pk_mul_f32 v[28:29], v[22:23], v[32:33] op_sel_hi:[1,0]
	v_pk_add_f32 v[6:7], v[6:7], v[30:31] op_sel_hi:[1,0] neg_lo:[0,1] neg_hi:[0,1]
	v_pk_add_f32 v[2:3], v[2:3], v[30:31] op_sel_hi:[1,0] neg_lo:[0,1] neg_hi:[0,1]
	v_pk_mul_f32 v[6:7], v[6:7], v[32:33] op_sel_hi:[1,0]
	v_pk_mul_f32 v[2:3], v[2:3], v[32:33] op_sel_hi:[1,0]
	s_waitcnt vmcnt(0)
	v_pk_fma_f32 v[22:23], v[18:19], v[24:25], v[36:37]
	v_pk_fma_f32 v[24:25], v[28:29], v[26:27], v[38:39]
	global_store_dwordx4 v[16:17], v[22:25], off offset:384
	global_load_dwordx4 v[26:29], v[12:13], off offset:400
	global_load_dwordx4 v[36:39], v[14:15], off offset:400
	v_pk_add_f32 v[18:19], v[20:21], v[30:31] op_sel_hi:[1,0] neg_lo:[0,1] neg_hi:[0,1]
	s_waitcnt vmcnt(0)
	v_pk_fma_f32 v[20:21], v[6:7], v[26:27], v[36:37]
	v_pk_mul_f32 v[40:41], v[18:19], v[32:33] op_sel_hi:[1,0]
	v_cvt_pk_bf16_f32 v18, v22, v23
	v_pk_fma_f32 v[22:23], v[40:41], v[28:29], v[38:39]
	v_cvt_pk_bf16_f32 v19, v24, v25
	global_store_dwordx4 v[16:17], v[20:23], off offset:400
	v_pk_add_f32 v[6:7], v[8:9], v[30:31] op_sel_hi:[1,0] neg_lo:[0,1] neg_hi:[0,1]
	s_nop 0
	v_cvt_pk_bf16_f32 v20, v20, v21
	v_cvt_pk_bf16_f32 v21, v22, v23
	global_store_dwordx4 v[34:35], v[18:21], off offset:192
	global_load_dwordx4 v[18:21], v[12:13], off offset:416
	s_nop 0
	global_load_dwordx4 v[22:25], v[14:15], off offset:416
	v_pk_mul_f32 v[8:9], v[6:7], v[32:33] op_sel_hi:[1,0]
	s_waitcnt vmcnt(0)
	v_pk_fma_f32 v[6:7], v[2:3], v[18:19], v[22:23]
	v_pk_fma_f32 v[8:9], v[8:9], v[20:21], v[24:25]
	global_store_dwordx4 v[16:17], v[6:9], off offset:416
	global_load_dwordx4 v[18:21], v[12:13], off offset:432
	s_nop 0
	global_load_dwordx4 v[12:15], v[14:15], off offset:432
	v_pk_add_f32 v[2:3], v[4:5], v[30:31] op_sel_hi:[1,0] neg_lo:[0,1] neg_hi:[0,1]
	v_pk_add_f32 v[4:5], v[10:11], v[30:31] op_sel_hi:[1,0] neg_lo:[0,1] neg_hi:[0,1]
	v_pk_mul_f32 v[10:11], v[2:3], v[32:33] op_sel_hi:[1,0]
	v_pk_mul_f32 v[22:23], v[4:5], v[32:33] op_sel_hi:[1,0]
	v_cvt_pk_bf16_f32 v2, v6, v7
	v_cvt_pk_bf16_f32 v3, v8, v9
	s_waitcnt vmcnt(0)
	v_pk_fma_f32 v[4:5], v[10:11], v[18:19], v[12:13]
	v_pk_fma_f32 v[6:7], v[22:23], v[20:21], v[14:15]
	global_store_dwordx4 v[16:17], v[4:7], off offset:432
	s_nop 1
	v_cvt_pk_bf16_f32 v4, v4, v5
	v_cvt_pk_bf16_f32 v5, v6, v7
	global_store_dwordx4 v[34:35], v[2:5], off offset:208
	s_barrier
	s_add_i32 s2, s35, 8
	s_cmp_gt_u32 s35, 7
	s_mov_b32 s35, s2
	s_cbranch_scc1 .LBB0_779
